# strategy 7.5 continued: remaining packed f32 ops (attention unit epilogues, rare rescale paths, prologue, final norm) split into single ops
# baseline (speedup 1.0000x reference)
; #define LAS __attribute__((address_space(3)))
; __device__ __forceinline__ int colmap_uq(int n) { if (n >= NUQ) return -1; const int hd = n / 192, d = n % 192; return hd * 192 + (d < 128 ? d : 128 + pairperm(d - 128, 64)); }
; template <int MAP>
; __device__ __forceinline__ void transpose_item(const float* W, int K, int Nsrc, int Ndst, bf16* WT, const float* gain, LAS float* scr, int item, int lane) {
;     const int nblk = Ndst / 32, kb = item / nblk, nb = item % nblk, k0 = 64 * kb, n0 = 32 * nb;
;     const int nn = n0 + (lane & 31); const int sc = MAP == 0 ? nn : (MAP == 1 ? colmap_in(nn) : colmap_uq(nn));
;     float wv_[32];
; #pragma unroll
;     for (int i = 0; i < 32; ++i) { const int kk = 2 * i + (lane >> 5); wv_[i] = (sc >= 0) ? W[(size_t)(k0 + kk) * Nsrc + sc] : 0.f; }
; #pragma unroll
;     for (int i = 0; i < 32; ++i) { const int kk = 2 * i + (lane >> 5); float v = wv_[i]; if (gain) v *= gain[k0 + kk]; scr[kk * 33 + (lane & 31)] = v; }
;     ...
;             if (r < I_UKV) { transpose_item<0>(ap->w_ukv + (size_t)L * KUKV * NUKV, KUKV, NUKV, NUKV, WUKV + (size_t)L * NUKV * KUKV, ap->kv_norm_g + L * KUKV, scr, r, lane); continue; } r -= I_UKV;
.LBB0_29:
	s_andn2_b64 vcc, exec, s[2:3]
	s_cbranch_vccnz .LBB0_43
	s_load_dwordx2 s[12:13], s[6:7], 0x28
	s_load_dwordx2 s[2:3], s[6:7], 0x48
	s_mul_i32 s14, s4, 0x180000
	s_mul_hi_i32 s5, s4, 0x180000
	s_waitcnt lgkmcnt(0)
	s_add_u32 s14, s12, s14
	s_addc_u32 s15, s13, s5
	s_lshl_b32 s12, s4, 8
	s_ashr_i32 s13, s12, 31
	s_lshl_b64 s[12:13], s[12:13], 2
	s_add_u32 s12, s2, s12
	s_addc_u32 s13, s3, s13
	s_add_i32 s5, s18, 16
	s_and_b32 s16, s5, 0xff
	s_mulk_i32 s16, 0xab
	s_bfe_u32 s16, s16, 0x3000d
	s_mul_i32 s17, s16, 48
	s_sub_i32 s5, s5, s17
	s_and_b32 s5, s5, 0xff
	s_lshl_b32 s16, s16, 6
	s_lshl_b32 s5, s5, 5
	v_or_b32_e32 v26, s16, v4
	v_or_b32_e32 v6, s5, v34
	v_mul_u32_u24_e32 v9, 0x600, v26
	v_add_lshl_u32 v6, v9, v6, 2
	v_lshl_add_u64 v[10:11], s[14:15], 0, v[6:7]
	s_movk_i32 s17, 0x3000
	v_add_co_u32_e32 v12, vcc, s17, v10
	s_movk_i32 s17, 0x6000
	s_nop 0
	v_addc_co_u32_e32 v13, vcc, 0, v11, vcc
	v_add_co_u32_e32 v14, vcc, s17, v10
	s_mov_b32 s17, 0xf000
	s_nop 0
	v_addc_co_u32_e32 v15, vcc, 0, v11, vcc
	v_add_co_u32_e32 v16, vcc, s66, v10
	s_cmp_lg_u64 s[2:3], 0
	s_nop 0
	v_addc_co_u32_e32 v17, vcc, 0, v11, vcc
	v_add_co_u32_e32 v18, vcc, s35, v10
	v_add_lshl_u32 v69, s16, v4, 2
	s_nop 0
	v_addc_co_u32_e32 v19, vcc, 0, v11, vcc
	v_add_co_u32_e32 v20, vcc, s17, v10
	s_mov_b32 s17, 0x12000
	s_nop 0
	v_addc_co_u32_e32 v21, vcc, 0, v11, vcc
	v_add_co_u32_e32 v22, vcc, s17, v10
	s_mov_b32 s17, 0x15000
	s_nop 0
	v_addc_co_u32_e32 v23, vcc, 0, v11, vcc
	v_add_co_u32_e32 v28, vcc, s17, v10
	s_mov_b32 s17, 0x1b000
	s_nop 0
	v_addc_co_u32_e32 v29, vcc, 0, v11, vcc
	v_add_co_u32_e32 v30, vcc, s38, v10
	s_nop 1
	v_addc_co_u32_e32 v31, vcc, 0, v11, vcc
	global_load_dword v71, v[12:13], off
	global_load_dword v72, v[14:15], off
	global_load_dword v73, v[16:17], off
	global_load_dword v24, v[18:19], off
	global_load_dword v25, v[20:21], off
	s_nop 0
	global_load_dword v22, v[22:23], off
	s_nop 0
	global_load_dword v23, v[28:29], off
	global_load_dword v63, v[30:31], off
	v_add_co_u32_e32 v12, vcc, s17, v10
	s_mov_b32 s17, 0x1e000
	s_nop 0
	v_addc_co_u32_e32 v13, vcc, 0, v11, vcc
	v_add_co_u32_e32 v14, vcc, s17, v10
	s_mov_b32 s17, 0x21000
	s_nop 0
	v_addc_co_u32_e32 v15, vcc, 0, v11, vcc
	v_add_co_u32_e32 v16, vcc, s17, v10
	s_mov_b32 s17, 0x27000
	s_nop 0
	v_addc_co_u32_e32 v17, vcc, 0, v11, vcc
	v_add_co_u32_e32 v18, vcc, s41, v10
	s_nop 1
	v_addc_co_u32_e32 v19, vcc, 0, v11, vcc
	v_add_co_u32_e32 v28, vcc, s17, v10
	s_mov_b32 s17, 0x2a000
	s_nop 0
	v_addc_co_u32_e32 v29, vcc, 0, v11, vcc
	v_add_co_u32_e32 v30, vcc, s17, v10
	s_mov_b32 s17, 0x2d000
	s_nop 0
	v_addc_co_u32_e32 v31, vcc, 0, v11, vcc
	v_add_co_u32_e32 v64, vcc, s17, v10
	s_mov_b32 s17, 0x33000
	s_nop 0
	v_addc_co_u32_e32 v65, vcc, 0, v11, vcc
	v_add_co_u32_e32 v74, vcc, s44, v10
	s_nop 1
	v_addc_co_u32_e32 v75, vcc, 0, v11, vcc
	global_load_dword v67, v[12:13], off
	global_load_dword v68, v[14:15], off
	global_load_dword v70, v[16:17], off
	global_load_dword v20, v[18:19], off
	global_load_dword v21, v[28:29], off
	s_nop 0
	global_load_dword v18, v[30:31], off
	global_load_dword v19, v[64:65], off
	s_nop 0
	global_load_dword v30, v[74:75], off
	v_add_co_u32_e32 v12, vcc, s17, v10
	s_mov_b32 s17, 0x36000
	s_nop 0
	v_addc_co_u32_e32 v13, vcc, 0, v11, vcc
	v_add_co_u32_e32 v14, vcc, s17, v10
	s_mov_b32 s17, 0x39000
	s_nop 0
	v_addc_co_u32_e32 v15, vcc, 0, v11, vcc
	v_add_co_u32_e32 v16, vcc, s17, v10
	s_mov_b32 s17, 0x3f000
	s_nop 0
	v_addc_co_u32_e32 v17, vcc, 0, v11, vcc
	v_add_co_u32_e32 v28, vcc, s47, v10
	s_nop 1
	v_addc_co_u32_e32 v29, vcc, 0, v11, vcc
	v_add_co_u32_e32 v74, vcc, s17, v10
	s_mov_b32 s17, 0x42000
	s_nop 0
	v_addc_co_u32_e32 v75, vcc, 0, v11, vcc
	v_add_co_u32_e32 v76, vcc, s17, v10
	s_mov_b32 s17, 0x45000
	s_nop 0
	v_addc_co_u32_e32 v77, vcc, 0, v11, vcc
	v_add_co_u32_e32 v78, vcc, s17, v10
	s_mov_b32 s17, 0x4b000
	s_nop 0
	v_addc_co_u32_e32 v79, vcc, 0, v11, vcc
	v_add_co_u32_e32 v80, vcc, s50, v10
	s_nop 1
	v_addc_co_u32_e32 v81, vcc, 0, v11, vcc
	global_load_dword v64, v[12:13], off
	global_load_dword v65, v[14:15], off
	global_load_dword v66, v[16:17], off
	s_nop 0
	global_load_dword v16, v[28:29], off
	global_load_dword v17, v[74:75], off
	global_load_dword v14, v[76:77], off
	global_load_dword v15, v[78:79], off
	global_load_dword v9, v[80:81], off
	v_add_co_u32_e32 v12, vcc, s17, v10
	s_mov_b32 s17, 0x4e000
	s_nop 0
	v_addc_co_u32_e32 v13, vcc, 0, v11, vcc
	v_add_co_u32_e32 v28, vcc, s17, v10
	s_mov_b32 s17, 0x51000
	s_nop 0
	v_addc_co_u32_e32 v29, vcc, 0, v11, vcc
	v_add_co_u32_e32 v76, vcc, s17, v10
	s_nop 1
	v_addc_co_u32_e32 v77, vcc, 0, v11, vcc
	v_add_co_u32_e32 v78, vcc, s53, v10
	s_nop 1
	v_addc_co_u32_e32 v79, vcc, 0, v11, vcc
	v_add_co_u32_e32 v80, vcc, 0x57000, v10
	s_nop 1
	v_addc_co_u32_e32 v81, vcc, 0, v11, vcc
	v_add_co_u32_e32 v82, vcc, 0x5a000, v10
	s_nop 1
	v_addc_co_u32_e32 v83, vcc, 0, v11, vcc
	v_add_co_u32_e32 v84, vcc, 0x5d000, v10
	s_nop 1
	v_addc_co_u32_e32 v85, vcc, 0, v11, vcc
	global_load_dword v74, v6, s[14:15]
	s_nop 0
	global_load_dword v6, v[12:13], off
	global_load_dword v31, v[28:29], off
	global_load_dword v62, v[76:77], off
	s_nop 0
	global_load_dword v12, v[78:79], off
	global_load_dword v13, v[80:81], off
	global_load_dword v10, v[82:83], off
	global_load_dword v11, v[84:85], off
	s_cselect_b64 s[14:15], -1, 0
	s_cmp_eq_u64 s[2:3], 0
	s_cbranch_scc1 .LBB0_246
	v_lshlrev_b32_e32 v28, 2, v26
	global_load_dword v29, v69, s[12:13] offset:8
	global_load_dword v75, v69, s[12:13] offset:16
	global_load_dword v78, v69, s[12:13] offset:24
	global_load_dword v26, v69, s[12:13] offset:32
	global_load_dword v27, v69, s[12:13] offset:40
	global_load_dword v76, v69, s[12:13] offset:48
	global_load_dword v77, v69, s[12:13] offset:56
	global_load_dword v79, v28, s[12:13]
	v_add_u32_e32 v80, v35, v42
	s_waitcnt vmcnt(7)
	v_mul_f32_e32 v81, v71, v29
	s_waitcnt vmcnt(6)
	v_mul_f32_e32 v75, v72, v75
	s_waitcnt vmcnt(5)
	v_mul_f32_e32 v78, v73, v78
	s_waitcnt vmcnt(3)
	v_mul_f32_e32 v28, v24, v26
	v_mul_f32_e32 v29, v25, v27
	s_waitcnt vmcnt(1)
	v_mul_f32_e32 v26, v22, v76
	v_mul_f32_e32 v27, v23, v77
	s_waitcnt vmcnt(0)
	v_mul_f32_e32 v76, v74, v79
	ds_write_b32 v36, v76
	ds_write2_b32 v80, v81, v75 offset1:66
	ds_write_b32 v80, v78 offset:528
	s_cbranch_execnz .LBB0_33

; #define LAS __attribute__((address_space(3)))
; __device__ __forceinline__ int colmap_uq(int n) { if (n >= NUQ) return -1; const int hd = n / 192, d = n % 192; return hd * 192 + (d < 128 ? d : 128 + pairperm(d - 128, 64)); }
; template <int MAP>
; __device__ __forceinline__ void transpose_item(const float* W, int K, int Nsrc, int Ndst, bf16* WT, const float* gain, LAS float* scr, int item, int lane) {
;     const int nblk = Ndst / 32, kb = item / nblk, nb = item % nblk, k0 = 64 * kb, n0 = 32 * nb;
;     const int nn = n0 + (lane & 31); const int sc = MAP == 0 ? nn : (MAP == 1 ? colmap_in(nn) : colmap_uq(nn));
;     float wv_[32];
; #pragma unroll
;     for (int i = 0; i < 32; ++i) { const int kk = 2 * i + (lane >> 5); wv_[i] = (sc >= 0) ? W[(size_t)(k0 + kk) * Nsrc + sc] : 0.f; }
; #pragma unroll
;     for (int i = 0; i < 32; ++i) { const int kk = 2 * i + (lane >> 5); float v = wv_[i]; if (gain) v *= gain[k0 + kk]; scr[kk * 33 + (lane & 31)] = v; }
;     ...
;             if (r < I_UKV) { transpose_item<0>(ap->w_ukv + (size_t)L * KUKV * NUKV, KUKV, NUKV, NUKV, WUKV + (size_t)L * NUKV * KUKV, ap->kv_norm_g + L * KUKV, scr, r, lane); continue; } r -= I_UKV;
.LBB0_33:
	s_waitcnt vmcnt(25)
	v_cndmask_b32_e64 v23, 0, 1, s[14:15]
	v_add_u32_e32 v22, v35, v43
	v_cmp_ne_u32_e64 s[2:3], 1, v23
	s_andn2_b64 vcc, exec, s[14:15]
	ds_write2_b32 v22, v28, v29 offset1:66
	ds_write2_b32 v22, v26, v27 offset0:132 offset1:198
	s_cbranch_vccnz .LBB0_247
	global_load_dword v26, v69, s[12:13] offset:64
	global_load_dword v27, v69, s[12:13] offset:72
	global_load_dword v28, v69, s[12:13] offset:80
	global_load_dword v29, v69, s[12:13] offset:88
	global_load_dword v22, v69, s[12:13] offset:96
	global_load_dword v23, v69, s[12:13] offset:104
	global_load_dword v24, v69, s[12:13] offset:112
	global_load_dword v25, v69, s[12:13] offset:120
	v_add_u32_e32 v71, v35, v44
	s_waitcnt vmcnt(7)
	v_mul_f32_e32 v26, v63, v26
	s_waitcnt vmcnt(6)
	v_mul_f32_e32 v27, v67, v27
	s_waitcnt vmcnt(5)
	v_mul_f32_e32 v28, v68, v28
	s_waitcnt vmcnt(4)
	v_mul_f32_e32 v29, v70, v29
	ds_write2_b32 v71, v26, v27 offset1:66
	ds_write2_b32 v71, v28, v29 offset0:132 offset1:198
	s_waitcnt vmcnt(2)
	v_mul_f32_e32 v22, v20, v22
	v_mul_f32_e32 v23, v21, v23
	s_waitcnt vmcnt(0)
	v_mul_f32_e32 v24, v18, v24
	v_mul_f32_e32 v25, v19, v25
	s_cbranch_execnz .LBB0_36

; #define LAS __attribute__((address_space(3)))
; __device__ __forceinline__ int colmap_uq(int n) { if (n >= NUQ) return -1; const int hd = n / 192, d = n % 192; return hd * 192 + (d < 128 ? d : 128 + pairperm(d - 128, 64)); }
; template <int MAP>
; __device__ __forceinline__ void transpose_item(const float* W, int K, int Nsrc, int Ndst, bf16* WT, const float* gain, LAS float* scr, int item, int lane) {
;     const int nblk = Ndst / 32, kb = item / nblk, nb = item % nblk, k0 = 64 * kb, n0 = 32 * nb;
;     const int nn = n0 + (lane & 31); const int sc = MAP == 0 ? nn : (MAP == 1 ? colmap_in(nn) : colmap_uq(nn));
;     float wv_[32];
; #pragma unroll
;     for (int i = 0; i < 32; ++i) { const int kk = 2 * i + (lane >> 5); wv_[i] = (sc >= 0) ? W[(size_t)(k0 + kk) * Nsrc + sc] : 0.f; }
; #pragma unroll
;     for (int i = 0; i < 32; ++i) { const int kk = 2 * i + (lane >> 5); float v = wv_[i]; if (gain) v *= gain[k0 + kk]; scr[kk * 33 + (lane & 31)] = v; }
;     ...
;             if (r < I_UKV) { transpose_item<0>(ap->w_ukv + (size_t)L * KUKV * NUKV, KUKV, NUKV, NUKV, WUKV + (size_t)L * NUKV * KUKV, ap->kv_norm_g + L * KUKV, scr, r, lane); continue; } r -= I_UKV;
.LBB0_36:
	s_waitcnt vmcnt(18)
	v_add_u32_e32 v18, v35, v45
	s_and_b64 vcc, exec, s[2:3]
	ds_write2_b32 v18, v22, v23 offset1:66
	ds_write2_b32 v18, v24, v25 offset0:132 offset1:198
	s_cbranch_vccnz .LBB0_248
	global_load_dword v22, v69, s[12:13] offset:128
	global_load_dword v23, v69, s[12:13] offset:136
	global_load_dword v24, v69, s[12:13] offset:144
	global_load_dword v25, v69, s[12:13] offset:152
	global_load_dword v18, v69, s[12:13] offset:160
	global_load_dword v19, v69, s[12:13] offset:168
	global_load_dword v20, v69, s[12:13] offset:176
	global_load_dword v21, v69, s[12:13] offset:184
	v_add_u32_e32 v26, v35, v46
	s_waitcnt vmcnt(7)
	v_mul_f32_e32 v22, v30, v22
	s_waitcnt vmcnt(6)
	v_mul_f32_e32 v23, v64, v23
	s_waitcnt vmcnt(5)
	v_mul_f32_e32 v24, v65, v24
	s_waitcnt vmcnt(4)
	v_mul_f32_e32 v25, v66, v25
	ds_write2_b32 v26, v22, v23 offset1:66
	ds_write2_b32 v26, v24, v25 offset0:132 offset1:198
	s_waitcnt vmcnt(2)
	v_mul_f32_e32 v18, v16, v18
	v_mul_f32_e32 v19, v17, v19
	s_waitcnt vmcnt(0)
	v_mul_f32_e32 v20, v14, v20
	v_mul_f32_e32 v21, v15, v21
	s_cbranch_execnz .LBB0_39

; #define LAS __attribute__((address_space(3)))
; __device__ __forceinline__ int colmap_uq(int n) { if (n >= NUQ) return -1; const int hd = n / 192, d = n % 192; return hd * 192 + (d < 128 ? d : 128 + pairperm(d - 128, 64)); }
; template <int MAP>
; __device__ __forceinline__ void transpose_item(const float* W, int K, int Nsrc, int Ndst, bf16* WT, const float* gain, LAS float* scr, int item, int lane) {
;     const int nblk = Ndst / 32, kb = item / nblk, nb = item % nblk, k0 = 64 * kb, n0 = 32 * nb;
;     const int nn = n0 + (lane & 31); const int sc = MAP == 0 ? nn : (MAP == 1 ? colmap_in(nn) : colmap_uq(nn));
;     float wv_[32];
; #pragma unroll
;     for (int i = 0; i < 32; ++i) { const int kk = 2 * i + (lane >> 5); wv_[i] = (sc >= 0) ? W[(size_t)(k0 + kk) * Nsrc + sc] : 0.f; }
; #pragma unroll
;     for (int i = 0; i < 32; ++i) { const int kk = 2 * i + (lane >> 5); float v = wv_[i]; if (gain) v *= gain[k0 + kk]; scr[kk * 33 + (lane & 31)] = v; }
;     ...
;             if (r < I_UKV) { transpose_item<0>(ap->w_ukv + (size_t)L * KUKV * NUKV, KUKV, NUKV, NUKV, WUKV + (size_t)L * NUKV * KUKV, ap->kv_norm_g + L * KUKV, scr, r, lane); continue; } r -= I_UKV;
.LBB0_39:
	s_waitcnt vmcnt(10)
	v_add_u32_e32 v14, v35, v47
	s_and_b64 vcc, exec, s[2:3]
	ds_write2_b32 v14, v18, v19 offset1:66
	ds_write2_b32 v14, v20, v21 offset0:132 offset1:198
	s_cbranch_vccnz .LBB0_249
	global_load_dword v18, v69, s[12:13] offset:192
	global_load_dword v19, v69, s[12:13] offset:200
	global_load_dword v20, v69, s[12:13] offset:208
	global_load_dword v21, v69, s[12:13] offset:216
	global_load_dword v14, v69, s[12:13] offset:224
	global_load_dword v15, v69, s[12:13] offset:232
	global_load_dword v16, v69, s[12:13] offset:240
	global_load_dword v17, v69, s[12:13] offset:248
	v_add_u32_e32 v22, v35, v48
	s_waitcnt vmcnt(7)
	v_mul_f32_e32 v18, v9, v18
	s_waitcnt vmcnt(6)
	v_mul_f32_e32 v19, v6, v19
	s_waitcnt vmcnt(5)
	v_mul_f32_e32 v20, v31, v20
	s_waitcnt vmcnt(4)
	v_mul_f32_e32 v21, v62, v21
	ds_write2_b32 v22, v18, v19 offset1:66
	ds_write2_b32 v22, v20, v21 offset0:132 offset1:198
	s_waitcnt vmcnt(2)
	v_mul_f32_e32 v14, v12, v14
	v_mul_f32_e32 v15, v13, v15
	s_waitcnt vmcnt(0)
	v_mul_f32_e32 v16, v10, v16
	v_mul_f32_e32 v17, v11, v17
	s_cbranch_execnz .LBB0_42

; #define LAS __attribute__((address_space(3)))
; __device__ __forceinline__ int colmap_uq(int n) { if (n >= NUQ) return -1; const int hd = n / 192, d = n % 192; return hd * 192 + (d < 128 ? d : 128 + pairperm(d - 128, 64)); }
; template <int MAP>
; __device__ __forceinline__ void transpose_item(const float* W, int K, int Nsrc, int Ndst, bf16* WT, const float* gain, LAS float* scr, int item, int lane) {
;     const int nblk = Ndst / 32, kb = item / nblk, nb = item % nblk, k0 = 64 * kb, n0 = 32 * nb;
;     const int nn = n0 + (lane & 31); const int sc = MAP == 0 ? nn : (MAP == 1 ? colmap_in(nn) : colmap_uq(nn));
;     float wv_[32];
; #pragma unroll
;     for (int i = 0; i < 32; ++i) { const int kk = 2 * i + (lane >> 5); wv_[i] = (sc >= 0) ? W[(size_t)(k0 + kk) * Nsrc + sc] : 0.f; }
; #pragma unroll
;     for (int i = 0; i < 32; ++i) { const int kk = 2 * i + (lane >> 5); float v = wv_[i]; if (gain) v *= gain[k0 + kk]; scr[kk * 33 + (lane & 31)] = v; }
;     ...
;             if (r < I_UQ) { transpose_item<2>(ap->w_uq + (size_t)L * KUQ * NUQ, KUQ, NUQ, NUQP, WUQ + (size_t)L * NUQP * KUQ, ap->q_norm_g + L * KUQ, scr, r, lane); continue; } r -= I_UQ;
.LBB0_111:
	s_or_b64 exec, exec, s[14:15]
	s_mul_i32 s2, s4, 0x180
	s_ashr_i32 s3, s2, 31
	s_lshl_b64 s[2:3], s[2:3], 2
	s_waitcnt lgkmcnt(0)
	s_add_u32 s14, s12, s2
	s_addc_u32 s15, s13, s3
	s_cmp_lg_u64 s[12:13], 0
	s_cselect_b64 s[16:17], -1, 0
	s_cmp_eq_u64 s[12:13], 0
	v_add_lshl_u32 v6, s19, v4, 2
	s_cbranch_scc1 .LBB0_242
	v_lshlrev_b32_e32 v28, 2, v26
	global_load_dword v29, v6, s[14:15] offset:8
	global_load_dword v75, v6, s[14:15] offset:16
	global_load_dword v78, v6, s[14:15] offset:24
	global_load_dword v26, v6, s[14:15] offset:32
	global_load_dword v27, v6, s[14:15] offset:40
	global_load_dword v76, v6, s[14:15] offset:48
	global_load_dword v77, v6, s[14:15] offset:56
	global_load_dword v79, v28, s[14:15]
	v_add_u32_e32 v80, v35, v42
	s_waitcnt vmcnt(7)
	v_mul_f32_e32 v81, v9, v29
	s_waitcnt vmcnt(6)
	v_mul_f32_e32 v75, v62, v75
	s_waitcnt vmcnt(5)
	v_mul_f32_e32 v78, v31, v78
	s_waitcnt vmcnt(3)
	v_mul_f32_e32 v28, v10, v26
	v_mul_f32_e32 v29, v11, v27
	s_waitcnt vmcnt(1)
	v_mul_f32_e32 v26, v12, v76
	v_mul_f32_e32 v27, v13, v77
	s_waitcnt vmcnt(0)
	v_mul_f32_e32 v76, v30, v79
	ds_write_b32 v36, v76
	ds_write2_b32 v80, v81, v75 offset1:66
	ds_write_b32 v80, v78 offset:528
	s_cbranch_execnz .LBB0_114

; template <int MAP>
; __device__ __forceinline__ void transpose_item(const float* W, int K, int Nsrc, int Ndst, bf16* WT, const float* gain, LAS float* scr, int item, int lane) {
;     ...
;     for (int i = 0; i < 32; ++i) { const int kk = 2 * i + (lane >> 5); wv_[i] = (sc >= 0) ? W[(size_t)(k0 + kk) * Nsrc + sc] : 0.f; }
; #pragma unroll
;     for (int i = 0; i < 32; ++i) { const int kk = 2 * i + (lane >> 5); float v = wv_[i]; if (gain) v *= gain[k0 + kk]; scr[kk * 33 + (lane & 31)] = v; }
;     asm volatile("s_waitcnt lgkmcnt(0)" ::: "memory");
.LBB0_114:
	s_waitcnt vmcnt(0)
	v_cndmask_b32_e64 v10, 0, 1, s[16:17]
	v_add_u32_e32 v9, v35, v43
	v_cmp_ne_u32_e64 s[2:3], 1, v10
	s_andn2_b64 vcc, exec, s[16:17]
	ds_write2_b32 v9, v28, v29 offset1:66
	ds_write2_b32 v9, v26, v27 offset0:132 offset1:198
	s_cbranch_vccnz .LBB0_243
	global_load_dword v9, v6, s[14:15] offset:64
	global_load_dword v26, v6, s[14:15] offset:72
	global_load_dword v27, v6, s[14:15] offset:80
	global_load_dword v28, v6, s[14:15] offset:88
	global_load_dword v10, v6, s[14:15] offset:96
	global_load_dword v11, v6, s[14:15] offset:104
	global_load_dword v12, v6, s[14:15] offset:112
	global_load_dword v13, v6, s[14:15] offset:120
	v_add_u32_e32 v29, v35, v44
	s_waitcnt vmcnt(7)
	v_mul_f32_e32 v9, v64, v9
	s_waitcnt vmcnt(6)
	v_mul_f32_e32 v26, v63, v26
	s_waitcnt vmcnt(5)
	v_mul_f32_e32 v27, v66, v27
	s_waitcnt vmcnt(4)
	v_mul_f32_e32 v28, v65, v28
	ds_write2_b32 v29, v9, v26 offset1:66
	ds_write2_b32 v29, v27, v28 offset0:132 offset1:198
	s_waitcnt vmcnt(2)
	v_mul_f32_e32 v10, v14, v10
	v_mul_f32_e32 v11, v15, v11
	s_waitcnt vmcnt(0)
	v_mul_f32_e32 v12, v16, v12
	v_mul_f32_e32 v13, v17, v13
	s_cbranch_execnz .LBB0_117

; template <int MAP>
; __device__ __forceinline__ void transpose_item(const float* W, int K, int Nsrc, int Ndst, bf16* WT, const float* gain, LAS float* scr, int item, int lane) {
;     ...
;     for (int i = 0; i < 32; ++i) { const int kk = 2 * i + (lane >> 5); wv_[i] = (sc >= 0) ? W[(size_t)(k0 + kk) * Nsrc + sc] : 0.f; }
; #pragma unroll
;     for (int i = 0; i < 32; ++i) { const int kk = 2 * i + (lane >> 5); float v = wv_[i]; if (gain) v *= gain[k0 + kk]; scr[kk * 33 + (lane & 31)] = v; }
;     asm volatile("s_waitcnt lgkmcnt(0)" ::: "memory");
.LBB0_117:
	v_add_u32_e32 v9, v35, v45
	s_and_b64 vcc, exec, s[2:3]
	ds_write2_b32 v9, v10, v11 offset1:66
	ds_write2_b32 v9, v12, v13 offset0:132 offset1:198
	s_cbranch_vccnz .LBB0_244
	global_load_dword v9, v6, s[14:15] offset:128
	global_load_dword v14, v6, s[14:15] offset:136
	global_load_dword v15, v6, s[14:15] offset:144
	global_load_dword v16, v6, s[14:15] offset:152
	global_load_dword v10, v6, s[14:15] offset:160
	global_load_dword v11, v6, s[14:15] offset:168
	global_load_dword v12, v6, s[14:15] offset:176
	global_load_dword v13, v6, s[14:15] offset:184
	v_add_u32_e32 v17, v35, v46
	s_waitcnt vmcnt(7)
	v_mul_f32_e32 v9, v68, v9
	s_waitcnt vmcnt(6)
	v_mul_f32_e32 v14, v67, v14
	s_waitcnt vmcnt(5)
	v_mul_f32_e32 v15, v70, v15
	s_waitcnt vmcnt(4)
	v_mul_f32_e32 v16, v69, v16
	ds_write2_b32 v17, v9, v14 offset1:66
	ds_write2_b32 v17, v15, v16 offset0:132 offset1:198
	s_waitcnt vmcnt(2)
	v_mul_f32_e32 v10, v18, v10
	v_mul_f32_e32 v11, v19, v11
	s_waitcnt vmcnt(0)
	v_mul_f32_e32 v12, v20, v12
	v_mul_f32_e32 v13, v21, v13
	s_cbranch_execnz .LBB0_120

; template <int MAP>
; __device__ __forceinline__ void transpose_item(const float* W, int K, int Nsrc, int Ndst, bf16* WT, const float* gain, LAS float* scr, int item, int lane) {
;     ...
;     for (int i = 0; i < 32; ++i) { const int kk = 2 * i + (lane >> 5); wv_[i] = (sc >= 0) ? W[(size_t)(k0 + kk) * Nsrc + sc] : 0.f; }
; #pragma unroll
;     for (int i = 0; i < 32; ++i) { const int kk = 2 * i + (lane >> 5); float v = wv_[i]; if (gain) v *= gain[k0 + kk]; scr[kk * 33 + (lane & 31)] = v; }
;     asm volatile("s_waitcnt lgkmcnt(0)" ::: "memory");
.LBB0_120:
	v_add_u32_e32 v9, v35, v47
	s_and_b64 vcc, exec, s[2:3]
	ds_write2_b32 v9, v10, v11 offset1:66
	ds_write2_b32 v9, v12, v13 offset0:132 offset1:198
	s_cbranch_vccnz .LBB0_245
	global_load_dword v9, v6, s[14:15] offset:192
	global_load_dword v14, v6, s[14:15] offset:200
	global_load_dword v15, v6, s[14:15] offset:208
	global_load_dword v16, v6, s[14:15] offset:216
	global_load_dword v10, v6, s[14:15] offset:224
	global_load_dword v11, v6, s[14:15] offset:232
	global_load_dword v12, v6, s[14:15] offset:240
	global_load_dword v13, v6, s[14:15] offset:248
	v_add_u32_e32 v6, v35, v48
	s_waitcnt vmcnt(7)
	v_mul_f32_e32 v9, v72, v9
	s_waitcnt vmcnt(6)
	v_mul_f32_e32 v14, v71, v14
	s_waitcnt vmcnt(5)
	v_mul_f32_e32 v15, v74, v15
	s_waitcnt vmcnt(4)
	v_mul_f32_e32 v16, v73, v16
	ds_write2_b32 v6, v9, v14 offset1:66
	ds_write2_b32 v6, v15, v16 offset0:132 offset1:198
	s_waitcnt vmcnt(2)
	v_mul_f32_e32 v10, v22, v10
	v_mul_f32_e32 v11, v23, v11
	s_waitcnt vmcnt(0)
	v_mul_f32_e32 v12, v24, v12
	v_mul_f32_e32 v13, v25, v13
	s_cbranch_execnz .LBB0_123

; template <int MAP>
; __device__ __forceinline__ void transpose_item(const float* W, int K, int Nsrc, int Ndst, bf16* WT, const float* gain, LAS float* scr, int item, int lane) {
;     ...
;     for (int i = 0; i < 32; ++i) { const int kk = 2 * i + (lane >> 5); wv_[i] = (sc >= 0) ? W[(size_t)(k0 + kk) * Nsrc + sc] : 0.f; }
; #pragma unroll
;     for (int i = 0; i < 32; ++i) { const int kk = 2 * i + (lane >> 5); float v = wv_[i]; if (gain) v *= gain[k0 + kk]; scr[kk * 33 + (lane & 31)] = v; }
;     asm volatile("s_waitcnt lgkmcnt(0)" ::: "memory");
.LBB0_227:
	s_or_b64 exec, exec, s[16:17]
	s_lshl_b32 s2, s4, 11
	s_ashr_i32 s3, s2, 31
	s_lshl_b64 s[2:3], s[2:3], 2
	s_add_u32 s16, s14, s2
	s_addc_u32 s17, s15, s3
	s_cmp_lg_u64 s[14:15], 0
	s_cselect_b64 s[18:19], -1, 0
	s_cmp_eq_u64 s[14:15], 0
	v_add_u32_e32 v16, v35, v42
	s_cbranch_scc1 .LBB0_238
	v_ashrrev_i32_e32 v11, 31, v10
	s_ashr_i32 s13, s12, 31
	v_lshl_add_u64 v[10:11], v[10:11], 2, s[16:17]
	v_lshl_add_u64 v[14:15], s[12:13], 0, v[4:5]
	v_lshl_add_u64 v[14:15], v[14:15], 2, s[16:17]
	global_load_dword v17, v[10:11], off
	global_load_dword v78, v[14:15], off offset:8
	global_load_dword v79, v[14:15], off offset:16
	global_load_dword v80, v[14:15], off offset:24
	s_nop 0
	global_load_dword v10, v[14:15], off offset:32
	global_load_dword v11, v[14:15], off offset:40
	global_load_dword v76, v[14:15], off offset:48
	global_load_dword v77, v[14:15], off offset:56
	s_waitcnt vmcnt(7)
	v_mul_f32_e32 v14, v6, v17
	s_waitcnt vmcnt(6)
	v_mul_f32_e32 v17, v9, v78
	s_waitcnt vmcnt(5)
	v_mul_f32_e32 v78, v63, v79
	ds_write_b32 v36, v14
	s_waitcnt vmcnt(4)
	v_mul_f32_e32 v79, v62, v80
	s_waitcnt vmcnt(2)
	v_mul_f32_e32 v10, v12, v10
	v_mul_f32_e32 v11, v13, v11
	ds_write2_b32 v16, v17, v78 offset1:66
	ds_write_b32 v16, v79 offset:528
	s_waitcnt vmcnt(0)
	v_mul_f32_e32 v14, v18, v76
	v_mul_f32_e32 v15, v19, v77
	s_cbranch_execnz .LBB0_230

; template <int MAP>
; __device__ __forceinline__ void transpose_item(const float* W, int K, int Nsrc, int Ndst, bf16* WT, const float* gain, LAS float* scr, int item, int lane) {
;     ...
;     for (int i = 0; i < 32; ++i) { const int kk = 2 * i + (lane >> 5); wv_[i] = (sc >= 0) ? W[(size_t)(k0 + kk) * Nsrc + sc] : 0.f; }
; #pragma unroll
;     for (int i = 0; i < 32; ++i) { const int kk = 2 * i + (lane >> 5); float v = wv_[i]; if (gain) v *= gain[k0 + kk]; scr[kk * 33 + (lane & 31)] = v; }
;     asm volatile("s_waitcnt lgkmcnt(0)" ::: "memory");
.LBB0_230:
	s_waitcnt vmcnt(0)
	v_add_u32_e32 v6, v35, v43
	ds_write2_b32 v6, v10, v11 offset1:66
	ds_write2_b32 v6, v14, v15 offset0:132 offset1:198
	v_cndmask_b32_e64 v6, 0, 1, s[18:19]
	v_cmp_ne_u32_e64 s[2:3], 1, v6
	s_andn2_b64 vcc, exec, s[18:19]
	v_add_u32_e32 v6, v35, v44
	s_cbranch_vccnz .LBB0_239
	s_ashr_i32 s13, s12, 31
	v_lshl_add_u64 v[10:11], s[12:13], 0, v[4:5]
	v_lshl_add_u64 v[10:11], v[10:11], 2, s[16:17]
	global_load_dword v9, v[10:11], off offset:64
	global_load_dword v16, v[10:11], off offset:72
	global_load_dword v17, v[10:11], off offset:80
	global_load_dword v18, v[10:11], off offset:88
	global_load_dword v12, v[10:11], off offset:96
	global_load_dword v13, v[10:11], off offset:104
	global_load_dword v14, v[10:11], off offset:112
	global_load_dword v15, v[10:11], off offset:120
	s_waitcnt vmcnt(7)
	v_mul_f32_e32 v9, v65, v9
	s_waitcnt vmcnt(6)
	v_mul_f32_e32 v16, v64, v16
	s_waitcnt vmcnt(5)
	v_mul_f32_e32 v17, v67, v17
	s_waitcnt vmcnt(4)
	v_mul_f32_e32 v18, v66, v18
	ds_write2_b32 v6, v9, v16 offset1:66
	ds_write2_b32 v6, v17, v18 offset0:132 offset1:198
	s_waitcnt vmcnt(2)
	v_mul_f32_e32 v10, v20, v12
	v_mul_f32_e32 v11, v21, v13
	s_waitcnt vmcnt(0)
	v_mul_f32_e32 v12, v22, v14
	v_mul_f32_e32 v13, v23, v15
	s_cbranch_execnz .LBB0_233

; template <int MAP>
; __device__ __forceinline__ void transpose_item(const float* W, int K, int Nsrc, int Ndst, bf16* WT, const float* gain, LAS float* scr, int item, int lane) {
;     ...
;     for (int i = 0; i < 32; ++i) { const int kk = 2 * i + (lane >> 5); wv_[i] = (sc >= 0) ? W[(size_t)(k0 + kk) * Nsrc + sc] : 0.f; }
; #pragma unroll
;     for (int i = 0; i < 32; ++i) { const int kk = 2 * i + (lane >> 5); float v = wv_[i]; if (gain) v *= gain[k0 + kk]; scr[kk * 33 + (lane & 31)] = v; }
;     asm volatile("s_waitcnt lgkmcnt(0)" ::: "memory");
.LBB0_233:
	v_add_u32_e32 v6, v35, v45
	ds_write2_b32 v6, v10, v11 offset1:66
	ds_write2_b32 v6, v12, v13 offset0:132 offset1:198
	s_and_b64 vcc, exec, s[2:3]
	v_add_u32_e32 v6, v35, v46
	s_cbranch_vccnz .LBB0_240
	s_ashr_i32 s13, s12, 31
	v_lshl_add_u64 v[10:11], s[12:13], 0, v[4:5]
	v_lshl_add_u64 v[10:11], v[10:11], 2, s[16:17]
	global_load_dword v9, v[10:11], off offset:128
	global_load_dword v16, v[10:11], off offset:136
	global_load_dword v17, v[10:11], off offset:144
	global_load_dword v18, v[10:11], off offset:152
	global_load_dword v12, v[10:11], off offset:160
	global_load_dword v13, v[10:11], off offset:168
	global_load_dword v14, v[10:11], off offset:176
	global_load_dword v15, v[10:11], off offset:184
	s_waitcnt vmcnt(7)
	v_mul_f32_e32 v9, v69, v9
	s_waitcnt vmcnt(6)
	v_mul_f32_e32 v16, v68, v16
	s_waitcnt vmcnt(5)
	v_mul_f32_e32 v17, v71, v17
	s_waitcnt vmcnt(4)
	v_mul_f32_e32 v18, v70, v18
	ds_write2_b32 v6, v9, v16 offset1:66
	ds_write2_b32 v6, v17, v18 offset0:132 offset1:198
	s_waitcnt vmcnt(2)
	v_mul_f32_e32 v10, v24, v12
	v_mul_f32_e32 v11, v25, v13
	s_waitcnt vmcnt(0)
	v_mul_f32_e32 v12, v26, v14
	v_mul_f32_e32 v13, v27, v15
	s_cbranch_execnz .LBB0_236

; template <int MAP>
; __device__ __forceinline__ void transpose_item(const float* W, int K, int Nsrc, int Ndst, bf16* WT, const float* gain, LAS float* scr, int item, int lane) {
;     ...
;     for (int i = 0; i < 32; ++i) { const int kk = 2 * i + (lane >> 5); wv_[i] = (sc >= 0) ? W[(size_t)(k0 + kk) * Nsrc + sc] : 0.f; }
; #pragma unroll
;     for (int i = 0; i < 32; ++i) { const int kk = 2 * i + (lane >> 5); float v = wv_[i]; if (gain) v *= gain[k0 + kk]; scr[kk * 33 + (lane & 31)] = v; }
;     asm volatile("s_waitcnt lgkmcnt(0)" ::: "memory");
.LBB0_236:
	v_add_u32_e32 v6, v35, v47
	ds_write2_b32 v6, v10, v11 offset1:66
	ds_write2_b32 v6, v12, v13 offset0:132 offset1:198
	s_and_b64 vcc, exec, s[2:3]
	v_add_u32_e32 v6, v35, v48
	s_cbranch_vccnz .LBB0_241
	s_ashr_i32 s13, s12, 31
	v_lshl_add_u64 v[10:11], s[12:13], 0, v[4:5]
	v_lshl_add_u64 v[10:11], v[10:11], 2, s[16:17]
	global_load_dword v9, v[10:11], off offset:192
	global_load_dword v16, v[10:11], off offset:200
	global_load_dword v17, v[10:11], off offset:208
	global_load_dword v18, v[10:11], off offset:216
	global_load_dword v12, v[10:11], off offset:224
	global_load_dword v13, v[10:11], off offset:232
	global_load_dword v14, v[10:11], off offset:240
	global_load_dword v15, v[10:11], off offset:248
	s_waitcnt vmcnt(7)
	v_mul_f32_e32 v9, v73, v9
	s_waitcnt vmcnt(6)
	v_mul_f32_e32 v16, v72, v16
	s_waitcnt vmcnt(5)
	v_mul_f32_e32 v17, v75, v17
	s_waitcnt vmcnt(4)
	v_mul_f32_e32 v18, v74, v18
	ds_write2_b32 v6, v9, v16 offset1:66
	ds_write2_b32 v6, v17, v18 offset0:132 offset1:198
	s_waitcnt vmcnt(2)
	v_mul_f32_e32 v10, v28, v12
	v_mul_f32_e32 v11, v29, v13
	s_waitcnt vmcnt(0)
	v_mul_f32_e32 v12, v30, v14
	v_mul_f32_e32 v13, v31, v15
	s_cbranch_execnz .LBB0_15
	s_branch .LBB0_14

;     ...
;             const int t = i / NTAB, j = i % NTAB; int nrot, fi; if (j < 32) { nrot = 64; fi = j; } else if (j < 48) { nrot = 32; fi = j - 32; } else { nrot = 16; fi = j - 48; }
;             const float e = (float)fi * (2.0f / (float)nrot); const float invf = 1.0f / powf(500000.0f, e);
;             const float ang = (float)ap->pos[t] * invf; const double rev = (double)ang * 0.15915494309189535; const float fr = (float)(rev - floor(rev));
;             TAB[i] = make_float2(__builtin_amdgcn_cosf(fr), __builtin_amdgcn_sinf(fr));
.LBB0_271:
	s_or_b64 exec, exec, s[2:3]
	v_div_scale_f32 v5, s[2:3], v3, v3, 2.0
	v_rcp_f32_e32 v7, v5
	v_cvt_f32_i32_e32 v6, v6
	v_fma_f32 v14, -v5, v7, 1.0
	v_fmac_f32_e32 v7, v14, v7
	v_div_scale_f32 v14, vcc, 2.0, v3, 2.0
	v_mul_f32_e32 v15, v14, v7
	v_fma_f32 v16, -v5, v15, v14
	v_fmac_f32_e32 v15, v16, v7
	v_fma_f32 v5, -v5, v15, v14
	v_div_fmas_f32 v5, v5, v7, v15
	v_div_fixup_f32 v3, v5, v3, 2.0
	v_mul_f32_e32 v3, v3, v6
	v_cmp_eq_f32_e32 vcc, 0, v3
	s_nop 1
	v_cndmask_b32_e64 v5, v8, 1.0, vcc
	v_frexp_mant_f32_e32 v6, v5
	v_cmp_gt_f32_e64 s[2:3], s18, v6
	s_nop 1
	v_cndmask_b32_e64 v7, 1.0, 2.0, s[2:3]
	v_mul_f32_e32 v6, v6, v7
	v_add_f32_e32 v15, 1.0, v6
	v_rcp_f32_e32 v20, v15
	v_add_f32_e32 v7, -1.0, v15
	v_sub_f32_e32 v17, v6, v7
	v_add_f32_e32 v7, -1.0, v6
	v_mul_f32_e32 v21, v7, v20
	v_mul_f32_e32 v14, v15, v21
	v_fma_f32 v16, v21, v15, -v14
	v_fmac_f32_e32 v16, v21, v17
	v_add_f32_e32 v6, v14, v16
	v_sub_f32_e32 v15, v7, v6
	v_add_f32_e64 v18, v6, -v14
	v_add_f32_e64 v19, v7, -v15
	v_mov_b32_e32 v17, v6
	v_add_f32_e64 v6, v18, -v16
	v_add_f32_e64 v7, v19, -v17
	s_nop 0
	v_add_f32_e32 v6, v6, v7
	v_add_f32_e32 v6, v15, v6
	v_mul_f32_e32 v7, v20, v6
	v_add_f32_e32 v6, v21, v7
	v_sub_f32_e32 v14, v6, v21
	v_sub_f32_e32 v22, v7, v14
	v_mul_f32_e32 v7, v6, v6
	v_fma_f32 v15, v6, v6, -v7
	v_add_f32_e32 v14, v22, v22
	v_fmac_f32_e32 v15, v6, v14
	v_add_f32_e32 v14, v7, v15
	v_fmamk_f32 v16, v14, 0x3e76c4e1, v9
	v_fmaak_f32 v16, v14, v16, 0x3ecccdef
	v_sub_f32_e32 v7, v14, v7
	v_sub_f32_e32 v23, v15, v7
	v_mul_f32_e32 v7, v14, v16
	v_fma_f32 v15, v14, v16, -v7
	v_fmac_f32_e32 v15, v23, v16
	v_add_f32_e32 v16, v7, v15
	v_add_f32_e32 v17, 0x3f2aaaaa, v16
	v_sub_f32_e32 v7, v16, v7
	v_sub_f32_e32 v7, v15, v7
	v_add_f32_e32 v15, 0xbf2aaaaa, v17
	v_add_f32_e32 v7, 0x31739010, v7
	v_sub_f32_e32 v15, v16, v15
	v_mul_f32_e32 v18, v6, v14
	v_mul_f32_e32 v19, v7, v15
	v_add_f32_e32 v20, v6, v14
	v_add_f32_e32 v21, v7, v15
	v_fma_f32 v16, v14, v6, -v18
	v_fmac_f32_e32 v16, v14, v22
	v_mov_b32_e32 v19, v21
	v_fmac_f32_e32 v16, v23, v6
	v_add_f32_e32 v14, v18, v16
	v_add_f32_e32 v15, v19, v17
	s_nop 0
	v_sub_f32_e32 v7, v14, v18
	v_cvt_f64_f32_e32 v[18:19], v5
	v_frexp_exp_i32_f64_e32 v5, v[18:19]
	v_subbrev_co_u32_e64 v5, s[2:3], 0, v5, s[2:3]
	v_cvt_f32_i32_e32 v5, v5
	v_sub_f32_e32 v7, v16, v7
	v_sub_f32_e32 v16, v17, v15
	v_add_f32_e32 v20, v21, v16
	v_mul_f32_e32 v16, v14, v15
	v_mul_f32_e32 v17, v15, v14
	v_ldexp_f32 v21, v6, 1
	v_fma_f32 v18, v14, v15, -v16
	v_fmac_f32_e32 v18, v14, v20
	v_mul_f32_e32 v14, 0x3f317218, v5
	v_fmac_f32_e32 v18, v7, v15
	v_fma_f32 v20, v5, s19, -v14
	v_fmac_f32_e32 v20, 0xb102e308, v5
	v_add_f32_e32 v15, v16, v18
	v_add_f32_e32 v6, v14, v20
	v_add_f32_e32 v7, v15, v21
	v_ldexp_f32 v5, v22, 1
	v_mov_b32_e32 v22, v15
	v_mov_b32_e32 v23, v7
	v_mov_b32_e32 v17, v21
	v_add_f32_e64 v16, v22, -v16
	v_add_f32_e64 v17, v23, -v17
	v_mov_b32_e32 v19, v15
	v_add_f32_e64 v16, v18, -v16
	v_add_f32_e64 v17, v19, -v17
	v_mov_b32_e32 v21, v6
	v_add_f32_e32 v5, v5, v16
	v_add_f32_e32 v15, v5, v17
	v_ashrrev_i32_e32 v5, 31, v4
	v_lshl_add_u64 v[4:5], v[4:5], 2, s[6:7]
	global_load_dword v24, v[4:5], off
	v_add_f32_e64 v16, v6, -v14
	v_add_f32_e64 v17, v7, -v15
	v_add_f32_e32 v18, v6, v14
	v_add_f32_e32 v19, v7, v15
	v_mov_b32_e32 v14, v15
	v_mov_b32_e32 v17, v19
	v_add_f32_e64 v4, v20, -v16
	v_add_f32_e64 v5, v21, -v17
	v_add_f32_e32 v16, v20, v16
	v_add_f32_e32 v17, v21, v17
	v_mov_b32_e32 v15, v6
	v_add_f32_e64 v20, v17, -v6
	v_add_f32_e64 v21, v16, -v7
	v_add_f32_e64 v22, v18, -v20
	v_add_f32_e64 v23, v19, -v20
	v_mov_b32_e32 v18, v19
	v_mov_b32_e32 v19, v17
	v_pk_mov_b32 v[20:21], v[6:7], v[20:21] op_sel:[1,0]
	v_mov_b32_e32 v22, v4
	v_add_f32_e64 v18, v18, -v20
	v_add_f32_e64 v19, v19, -v21
	v_mov_b32_e32 v5, v17
	v_add_f32_e64 v6, v14, -v18
	v_add_f32_e64 v7, v15, -v19
	s_nop 0
	v_add_f32_e32 v14, v22, v6
	v_add_f32_e32 v15, v23, v7
	s_nop 0
	v_add_f32_e32 v18, v14, v15
	v_add_f32_e32 v19, v15, v14
	s_nop 0
	v_pk_add_f32 v[16:17], v[16:17], v[18:19] op_sel:[1,0] op_sel_hi:[0,1]
	v_mov_b32_e32 v15, v16
	v_add_f32_e64 v20, v14, -v4
	v_add_f32_e64 v21, v15, -v5
	v_mov_b32_e32 v7, v18
	v_sub_f32_e32 v5, v14, v20
	v_add_f32_e64 v6, v6, -v20
	v_add_f32_e64 v7, v7, -v21
	v_sub_f32_e32 v4, v4, v5
	v_add_f32_e32 v4, v6, v4
	v_add_f32_e32 v4, v4, v7
	v_add_f32_e32 v5, v16, v4
	v_sub_f32_e32 v6, v5, v16
	v_sub_f32_e32 v4, v4, v6
	v_mul_f32_e32 v6, v3, v5
	v_fma_f32 v5, v3, v5, -v6
	v_fmac_f32_e32 v5, v3, v4
	v_add_f32_e32 v4, v6, v5
	v_cmp_class_f32_e64 s[2:3], v6, s20
	v_sub_f32_e32 v7, v4, v6
	v_sub_f32_e32 v5, v5, v7
	v_cndmask_b32_e64 v4, v4, v6, s[2:3]
	v_cmp_eq_f32_e64 s[2:3], s22, v4
	s_nop 1
	v_cndmask_b32_e64 v6, 0, v10, s[2:3]
	v_sub_f32_e32 v7, v4, v6
	v_mul_f32_e32 v14, 0x3fb8aa3b, v7
	v_fma_f32 v15, v7, s23, -v14
	v_rndne_f32_e32 v16, v14
	v_fmac_f32_e32 v15, 0x32a5705f, v7
	v_sub_f32_e32 v14, v14, v16
	v_add_f32_e32 v14, v14, v15
	v_exp_f32_e32 v14, v14
	v_cvt_i32_f32_e32 v15, v16
	v_cmp_neq_f32_e64 s[2:3], |v4|, s21
	s_nop 1
	v_cndmask_b32_e64 v4, 0, v5, s[2:3]
	v_ldexp_f32 v5, v14, v15
	v_cmp_ngt_f32_e64 s[2:3], s24, v7
	v_add_f32_e32 v4, v6, v4
	s_nop 0
	v_cndmask_b32_e64 v5, 0, v5, s[2:3]
	v_cmp_nlt_f32_e64 s[2:3], s22, v7
	s_nop 1
	v_cndmask_b32_e64 v5, v11, v5, s[2:3]
	v_fma_f32 v4, v5, v4, v5
	v_cmp_class_f32_e64 s[2:3], v5, s20
	s_nop 1
	v_cndmask_b32_e64 v4, v4, v5, s[2:3]
	v_cmp_neq_f32_e64 s[2:3], v3, |v3|
	s_nop 1
	v_cndmask_b32_e64 v5, v11, 0, s[2:3]
	v_cndmask_b32_e64 v5, v5, 1.0, vcc
	v_cmp_class_f32_e64 s[2:3], v3, s20
	s_nop 1
	v_cndmask_b32_e64 v4, |v4|, v5, s[2:3]
	v_div_scale_f32 v5, s[2:3], v4, v4, 1.0
	v_rcp_f32_e32 v6, v5
	s_nop 0
	v_fma_f32 v7, -v5, v6, 1.0
	v_fmac_f32_e32 v6, v7, v6
	v_div_scale_f32 v7, vcc, 1.0, v4, 1.0
	v_mul_f32_e32 v14, v7, v6
	v_fma_f32 v15, -v5, v14, v7
	v_fmac_f32_e32 v14, v15, v6
	v_fma_f32 v5, -v5, v14, v7
	v_div_fmas_f32 v5, v5, v6, v14
	s_waitcnt vmcnt(0)
	v_cvt_f32_i32_e32 v6, v24
	v_div_fixup_f32 v4, v5, v4, 1.0
	v_cmp_o_f32_e32 vcc, v3, v3
	s_nop 1
	v_cndmask_b32_e32 v3, v13, v4, vcc
	v_mul_f32_e32 v3, v3, v6
	v_cvt_f64_f32_e32 v[4:5], v3
	v_mul_f64 v[6:7], v[4:5], s[12:13]
	v_floor_f64_e32 v[6:7], v[6:7]
	v_fma_f64 v[4:5], v[4:5], s[12:13], -v[6:7]
	v_cvt_f32_f64_e32 v3, v[4:5]
	v_cos_f32_e32 v4, v3
	v_sin_f32_e32 v5, v3
	v_ashrrev_i32_e32 v3, 31, v2
	v_lshl_add_u64 v[6:7], v[2:3], 3, s[8:9]
	v_add_u32_e32 v2, s82, v2
	v_cmp_lt_i32_e32 vcc, s25, v2
	s_or_b64 s[10:11], vcc, s[10:11]
	global_store_dwordx2 v[6:7], v[4:5], off
	s_andn2_b64 exec, exec, s[10:11]
	s_cbranch_execz .LBB0_277

; __device__ __forceinline__ unsigned cvtpk(float lo, float hi) { unsigned r; asm("v_cvt_pk_bf16_f32 %0, %1, %2" : "=v"(r) : "v"(lo), "v"(hi)); return r; }
; template <bool MASKED>
; __device__ __forceinline__ void softmax_tile(f32x16& s0, f32x16& s1, float& m, float& l, float& alpha, unsigned mlo, unsigned mhi, bf16x8 (&pk)[4]) {
;     ...
;     float sum = 0.f;
; #pragma unroll
;     for (int r = 0; r < 16; ++r) {
;         float p0 = __builtin_amdgcn_exp2f(s0[r] - mn), p1 = __builtin_amdgcn_exp2f(s1[r] - mn);
;         if (MASKED) { if (s0[r] <= -1e29f) p0 = 0.f; if (s1[r] <= -1e29f) p1 = 0.f; }
;         s0[r] = p0; s1[r] = p1; sum += p0 + p1;
;     }
;     l = l * alpha + sum;
; #pragma unroll
;     for (int k2 = 0; k2 < 2; ++k2) {
;         u32x4 a, b;
;         a.x = cvtpk(s0[8 * k2 + 0], s0[8 * k2 + 1]); a.y = cvtpk(s0[8 * k2 + 2], s0[8 * k2 + 3]); a.z = cvtpk(s0[8 * k2 + 4], s0[8 * k2 + 5]); a.w = cvtpk(s0[8 * k2 + 6], s0[8 * k2 + 7]);
;         b.x = cvtpk(s1[8 * k2 + 0], s1[8 * k2 + 1]); b.y = cvtpk(s1[8 * k2 + 2], s1[8 * k2 + 3]); b.z = cvtpk(s1[8 * k2 + 4], s1[8 * k2 + 5]); b.w = cvtpk(s1[8 * k2 + 6], s1[8 * k2 + 7]);
;         pk[k2] = __builtin_bit_cast(bf16x8, a); pk[2 + k2] = __builtin_bit_cast(bf16x8, b);
;     }
.Lm2_cfast:
	v_exp_f32_e32 v82, v82
	v_exp_f32_e32 v83, v83
	v_exp_f32_e32 v84, v84
	v_exp_f32_e32 v85, v85
	v_exp_f32_e32 v86, v86
	v_exp_f32_e32 v87, v87
	v_exp_f32_e32 v88, v88
	v_exp_f32_e32 v89, v89
	v_exp_f32_e32 v90, v90
	v_exp_f32_e32 v91, v91
	v_exp_f32_e32 v92, v92
	v_exp_f32_e32 v93, v93
	v_exp_f32_e32 v94, v94
	v_exp_f32_e32 v95, v95
	v_exp_f32_e32 v96, v96
	v_exp_f32_e32 v97, v97
	v_exp_f32_e32 v66, v66
	v_exp_f32_e32 v67, v67
	v_exp_f32_e32 v68, v68
	v_exp_f32_e32 v69, v69
	v_exp_f32_e32 v70, v70
	v_exp_f32_e32 v71, v71
	v_exp_f32_e32 v72, v72
	v_exp_f32_e32 v73, v73
	v_exp_f32_e32 v74, v74
	v_exp_f32_e32 v75, v75
	v_exp_f32_e32 v76, v76
	v_exp_f32_e32 v77, v77
	v_exp_f32_e32 v78, v78
	v_exp_f32_e32 v79, v79
	v_exp_f32_e32 v80, v80
	v_exp_f32_e32 v81, v81
	v_add_f32_e32 v150, v82, v84
	v_add_f32_e32 v151, v83, v85
	v_add_f32_e32 v152, v86, v88
	v_add_f32_e32 v153, v87, v89
	v_add_f32_e32 v154, v90, v92
	v_add_f32_e32 v155, v91, v93
	v_add_f32_e32 v156, v94, v96
	v_add_f32_e32 v157, v95, v97
	v_add_f32_e32 v158, v66, v68
	v_add_f32_e32 v159, v67, v69
	v_add_f32_e32 v160, v70, v72
	v_add_f32_e32 v161, v71, v73
	v_add_f32_e32 v162, v74, v76
	v_add_f32_e32 v163, v75, v77
	v_add_f32_e32 v164, v78, v80
	v_add_f32_e32 v165, v79, v81
	v_add_f32_e32 v150, v150, v152
	v_add_f32_e32 v151, v151, v153
	v_add_f32_e32 v154, v154, v156
	v_add_f32_e32 v155, v155, v157
	v_add_f32_e32 v158, v158, v160
	v_add_f32_e32 v159, v159, v161
	v_add_f32_e32 v162, v162, v164
	v_add_f32_e32 v163, v163, v165
	v_add_f32_e32 v150, v150, v154
	v_add_f32_e32 v151, v151, v155
	v_add_f32_e32 v158, v158, v162
	v_add_f32_e32 v159, v159, v163
	v_add_f32_e32 v150, v150, v158
	v_add_f32_e32 v151, v151, v159
	v_add_f32_e32 v164, v150, v151
	v_cvt_pk_bf16_f32 v66, v66, v67
	v_cvt_pk_bf16_f32 v67, v68, v69
	v_cvt_pk_bf16_f32 v68, v70, v71
	v_cvt_pk_bf16_f32 v69, v72, v73
	v_cvt_pk_bf16_f32 v70, v74, v75
	v_cvt_pk_bf16_f32 v71, v76, v77
	v_cvt_pk_bf16_f32 v72, v78, v79
	v_cvt_pk_bf16_f32 v73, v80, v81
	v_cvt_pk_bf16_f32 v74, v82, v83
	v_cvt_pk_bf16_f32 v75, v84, v85
	v_cvt_pk_bf16_f32 v76, v86, v87
	v_cvt_pk_bf16_f32 v77, v88, v89
	v_cvt_pk_bf16_f32 v78, v90, v91
	v_cvt_pk_bf16_f32 v79, v92, v93
	v_cvt_pk_bf16_f32 v80, v94, v95
	v_cvt_pk_bf16_f32 v81, v96, v97
	v_fmac_f32_e32 v164, v147, v0
	v_cmp_neq_f32_e32 vcc, 1.0, v0
	s_cbranch_vccz .LBB0_629
	v_mul_f32_e32 v64, v64, v0
	v_mul_f32_e32 v65, v65, v0
	v_mul_f32_e32 v62, v62, v0
	v_mul_f32_e32 v63, v63, v0
	v_mul_f32_e32 v60, v60, v0
	v_mul_f32_e32 v61, v61, v0
	v_mul_f32_e32 v58, v58, v0
	v_mul_f32_e32 v59, v59, v0
	v_mul_f32_e32 v56, v56, v0
	v_mul_f32_e32 v57, v57, v0
	v_mul_f32_e32 v54, v54, v0
	v_mul_f32_e32 v55, v55, v0
	v_mul_f32_e32 v52, v52, v0
	v_mul_f32_e32 v53, v53, v0
	v_mul_f32_e32 v50, v50, v0
	v_mul_f32_e32 v51, v51, v0
	v_mul_f32_e32 v48, v48, v0
	v_mul_f32_e32 v49, v49, v0
	v_mul_f32_e32 v46, v46, v0
	v_mul_f32_e32 v47, v47, v0
	v_mul_f32_e32 v44, v44, v0
	v_mul_f32_e32 v45, v45, v0
	v_mul_f32_e32 v42, v42, v0
	v_mul_f32_e32 v43, v43, v0
	v_mul_f32_e32 v40, v40, v0
	v_mul_f32_e32 v41, v41, v0
	v_mul_f32_e32 v38, v38, v0
	v_mul_f32_e32 v39, v39, v0
	v_mul_f32_e32 v36, v36, v0
	v_mul_f32_e32 v37, v37, v0
	v_mul_f32_e32 v34, v34, v0
	v_mul_f32_e32 v35, v35, v0
	v_mul_f32_e32 v32, v32, v0
	v_mul_f32_e32 v33, v33, v0
	v_mul_f32_e32 v30, v30, v0
	v_mul_f32_e32 v31, v31, v0
	v_mul_f32_e32 v28, v28, v0
	v_mul_f32_e32 v29, v29, v0
	v_mul_f32_e32 v26, v26, v0
	v_mul_f32_e32 v27, v27, v0
	v_mul_f32_e32 v24, v24, v0
	v_mul_f32_e32 v25, v25, v0
	v_mul_f32_e32 v22, v22, v0
	v_mul_f32_e32 v23, v23, v0
	v_mul_f32_e32 v20, v20, v0
	v_mul_f32_e32 v21, v21, v0
	v_mul_f32_e32 v18, v18, v0
	v_mul_f32_e32 v19, v19, v0
	v_mul_f32_e32 v16, v16, v0
	v_mul_f32_e32 v17, v17, v0
	v_mul_f32_e32 v14, v14, v0
	v_mul_f32_e32 v15, v15, v0
	v_mul_f32_e32 v12, v12, v0
	v_mul_f32_e32 v13, v13, v0
	v_mul_f32_e32 v10, v10, v0
	v_mul_f32_e32 v11, v11, v0
	v_mul_f32_e32 v8, v8, v0
	v_mul_f32_e32 v9, v9, v0
	v_mul_f32_e32 v6, v6, v0
	v_mul_f32_e32 v7, v7, v0
	v_mul_f32_e32 v4, v4, v0
	v_mul_f32_e32 v5, v5, v0
	v_mul_f32_e32 v2, v2, v0
	v_mul_f32_e32 v3, v3, v0

; __device__ __forceinline__ float sum_x32(float v) { const unsigned u = __float_as_uint(v); auto r = __builtin_amdgcn_permlane32_swap(u, u, false, false); return __uint_as_float(r[0]) + __uint_as_float(r[1]); }
; template <int MODE>
; __device__ __forceinline__ void attn_unit(LAS char* lds, const AttnPtrs& A, int b, int qb) {
;     ...
;         if (strm == 0) { float ss = 0.f;
; #pragma unroll
;             for (int c = 0; c < 4; ++c)
; #pragma unroll
;                 for (int r = 0; r < 16; ++r) { const float v = o1[c][r] * i1 - xb[(c * 16 + r) * 64]; o1[c][r] = v; ss += v * v; }
;             ss = sum_x32(ss); rstd = __builtin_amdgcn_rsqf(ss * (1.0f / 128.0f) + 1e-6f) * A.c_out; }
.LBB0_637:
	v_cndmask_b32_e64 v67, 0, 1, s[6:7]
	v_cmp_ne_u32_e64 s[2:3], 1, v67
	s_andn2_b64 vcc, exec, s[6:7]
	v_mov_b32_e32 v68, 1.0
	s_waitcnt vmcnt(0) lgkmcnt(0)
	s_barrier
	s_cbranch_vccnz .LBB0_639
	ds_read2st64_b32 v[68:69], v66 offset1:1
	ds_read2st64_b32 v[70:71], v66 offset0:2 offset1:3
	s_waitcnt lgkmcnt(1)
	v_fma_f32 v50, v50, v0, -v68
	v_fma_f32 v51, v51, v0, -v69
	s_nop 0
	v_mul_f32_e32 v68, v51, v51
	v_fma_f32 v69, v51, v51, v68
	v_fma_f32 v68, v50, v50, v68
	s_waitcnt lgkmcnt(0)
	v_fma_f32 v52, v52, v0, -v70
	v_fma_f32 v53, v53, v0, -v71
	s_nop 0
	v_fma_f32 v68, v52, v52, v68
	v_fma_f32 v69, v53, v53, v69
	v_mul_f32_e32 v70, v53, v53
	v_add_f32_e32 v68, v68, v70
	v_add_f32_e32 v69, v69, v70
	ds_read2st64_b32 v[70:71], v66 offset0:4 offset1:5
	s_waitcnt lgkmcnt(0)
	v_fma_f32 v54, v54, v0, -v70
	v_fma_f32 v55, v55, v0, -v71
	s_nop 0
	v_fma_f32 v68, v54, v54, v68
	v_fma_f32 v69, v55, v55, v69
	v_mul_f32_e32 v70, v55, v55
	v_add_f32_e32 v68, v68, v70
	v_add_f32_e32 v69, v69, v70
	ds_read2st64_b32 v[70:71], v66 offset0:6 offset1:7
	s_waitcnt lgkmcnt(0)
	v_fma_f32 v56, v56, v0, -v70
	v_fma_f32 v57, v57, v0, -v71
	s_nop 0
	v_fma_f32 v68, v56, v56, v68
	v_fma_f32 v69, v57, v57, v69
	v_mul_f32_e32 v70, v57, v57
	v_add_f32_e32 v68, v68, v70
	v_add_f32_e32 v69, v69, v70
	ds_read2st64_b32 v[70:71], v66 offset0:8 offset1:9
	s_waitcnt lgkmcnt(0)
	v_fma_f32 v58, v58, v0, -v70
	v_fma_f32 v59, v59, v0, -v71
	s_nop 0
	v_fma_f32 v68, v58, v58, v68
	v_fma_f32 v69, v59, v59, v69
	v_mul_f32_e32 v70, v59, v59
	v_add_f32_e32 v68, v68, v70
	v_add_f32_e32 v69, v69, v70
	ds_read2st64_b32 v[70:71], v66 offset0:10 offset1:11
	s_waitcnt lgkmcnt(0)
	v_fma_f32 v60, v60, v0, -v70
	v_fma_f32 v61, v61, v0, -v71
	s_nop 0
	v_fma_f32 v68, v60, v60, v68
	v_fma_f32 v69, v61, v61, v69
	v_mul_f32_e32 v70, v61, v61
	v_add_f32_e32 v68, v68, v70
	v_add_f32_e32 v69, v69, v70
	ds_read2st64_b32 v[70:71], v66 offset0:12 offset1:13
	s_waitcnt lgkmcnt(0)
	v_fma_f32 v62, v62, v0, -v70
	v_fma_f32 v63, v63, v0, -v71
	s_nop 0
	v_fma_f32 v68, v62, v62, v68
	v_fma_f32 v69, v63, v63, v69
	v_mul_f32_e32 v70, v63, v63
	v_add_f32_e32 v68, v68, v70
	v_add_f32_e32 v69, v69, v70
	ds_read2st64_b32 v[70:71], v66 offset0:14 offset1:15
	s_waitcnt lgkmcnt(0)
	v_fma_f32 v64, v64, v0, -v70
	v_fma_f32 v65, v65, v0, -v71
	s_nop 0
	v_fma_f32 v68, v64, v64, v68
	v_fma_f32 v69, v65, v65, v69
	v_mul_f32_e32 v70, v65, v65
	v_add_f32_e32 v68, v68, v70
	v_add_f32_e32 v69, v69, v70
	ds_read2st64_b32 v[70:71], v66 offset0:16 offset1:17
	s_waitcnt lgkmcnt(0)
	v_fma_f32 v34, v34, v0, -v70
	v_fma_f32 v35, v35, v0, -v71
	s_nop 0
	v_fma_f32 v68, v34, v34, v68
	v_fma_f32 v69, v35, v35, v69
	v_mul_f32_e32 v70, v35, v35
	v_add_f32_e32 v68, v68, v70
	v_add_f32_e32 v69, v69, v70
	ds_read2st64_b32 v[70:71], v66 offset0:18 offset1:19
	s_waitcnt lgkmcnt(0)
	v_fma_f32 v36, v36, v0, -v70
	v_fma_f32 v37, v37, v0, -v71
	s_nop 0
	v_fma_f32 v68, v36, v36, v68
	v_fma_f32 v69, v37, v37, v69
	v_mul_f32_e32 v70, v37, v37
	v_add_f32_e32 v68, v68, v70
	v_add_f32_e32 v69, v69, v70
	ds_read2st64_b32 v[70:71], v66 offset0:20 offset1:21
	s_waitcnt lgkmcnt(0)
	v_fma_f32 v38, v38, v0, -v70
	v_fma_f32 v39, v39, v0, -v71
	s_nop 0
	v_fma_f32 v68, v38, v38, v68
	v_fma_f32 v69, v39, v39, v69
	v_mul_f32_e32 v70, v39, v39
	v_add_f32_e32 v68, v68, v70
	v_add_f32_e32 v69, v69, v70
	ds_read2st64_b32 v[70:71], v66 offset0:22 offset1:23
	s_waitcnt lgkmcnt(0)
	v_fma_f32 v40, v40, v0, -v70
	v_fma_f32 v41, v41, v0, -v71
	s_nop 0
	v_fma_f32 v68, v40, v40, v68
	v_fma_f32 v69, v41, v41, v69
	v_mul_f32_e32 v70, v41, v41
	v_add_f32_e32 v68, v68, v70
	v_add_f32_e32 v69, v69, v70
	ds_read2st64_b32 v[70:71], v66 offset0:24 offset1:25
	s_waitcnt lgkmcnt(0)
	v_fma_f32 v42, v42, v0, -v70
	v_fma_f32 v43, v43, v0, -v71
	s_nop 0
	v_fma_f32 v68, v42, v42, v68
	v_fma_f32 v69, v43, v43, v69
	v_mul_f32_e32 v70, v43, v43
	v_add_f32_e32 v68, v68, v70
	v_add_f32_e32 v69, v69, v70
	ds_read2st64_b32 v[70:71], v66 offset0:26 offset1:27
	s_waitcnt lgkmcnt(0)
	v_fma_f32 v44, v44, v0, -v70
	v_fma_f32 v45, v45, v0, -v71
	s_nop 0
	v_fma_f32 v68, v44, v44, v68
	v_fma_f32 v69, v45, v45, v69
	v_mul_f32_e32 v70, v45, v45
	v_add_f32_e32 v68, v68, v70
	v_add_f32_e32 v69, v69, v70
	ds_read2st64_b32 v[70:71], v66 offset0:28 offset1:29
	s_waitcnt lgkmcnt(0)
	v_fma_f32 v46, v46, v0, -v70
	v_fma_f32 v47, v47, v0, -v71
	s_nop 0
	v_fma_f32 v68, v46, v46, v68
	v_fma_f32 v69, v47, v47, v69
	v_mul_f32_e32 v70, v47, v47
	v_add_f32_e32 v68, v68, v70
	v_add_f32_e32 v69, v69, v70
	ds_read2st64_b32 v[70:71], v66 offset0:30 offset1:31
	s_waitcnt lgkmcnt(0)
	v_fma_f32 v48, v48, v0, -v70
	v_fma_f32 v49, v49, v0, -v71
	s_nop 0
	v_fma_f32 v68, v48, v48, v68
	v_fma_f32 v69, v49, v49, v69
	v_mul_f32_e32 v70, v49, v49
	v_add_f32_e32 v68, v68, v70
	v_add_f32_e32 v69, v69, v70
	ds_read2st64_b32 v[70:71], v66 offset0:32 offset1:33
	s_waitcnt lgkmcnt(0)
; __device__ __forceinline__ float sum_x32(float v) { const unsigned u = __float_as_uint(v); auto r = __builtin_amdgcn_permlane32_swap(u, u, false, false); return __uint_as_float(r[0]) + __uint_as_float(r[1]); }
; template <int MODE>
; __device__ __forceinline__ void attn_unit(LAS char* lds, const AttnPtrs& A, int b, int qb) {
;     ...
;         if (strm == 0) { float ss = 0.f;
; #pragma unroll
;             for (int c = 0; c < 4; ++c)
; #pragma unroll
;                 for (int r = 0; r < 16; ++r) { const float v = o1[c][r] * i1 - xb[(c * 16 + r) * 64]; o1[c][r] = v; ss += v * v; }
;             ss = sum_x32(ss); rstd = __builtin_amdgcn_rsqf(ss * (1.0f / 128.0f) + 1e-6f) * A.c_out; }
	v_fma_f32 v18, v18, v0, -v70
	v_fma_f32 v19, v19, v0, -v71
	s_nop 0
	v_fma_f32 v68, v18, v18, v68
	v_fma_f32 v69, v19, v19, v69
	v_mul_f32_e32 v70, v19, v19
	v_add_f32_e32 v68, v68, v70
	v_add_f32_e32 v69, v69, v70
	ds_read2st64_b32 v[70:71], v66 offset0:34 offset1:35
	s_waitcnt lgkmcnt(0)
	v_fma_f32 v20, v20, v0, -v70
	v_fma_f32 v21, v21, v0, -v71
	s_nop 0
	v_fma_f32 v68, v20, v20, v68
	v_fma_f32 v69, v21, v21, v69
	v_mul_f32_e32 v70, v21, v21
	v_add_f32_e32 v68, v68, v70
	v_add_f32_e32 v69, v69, v70
	ds_read2st64_b32 v[70:71], v66 offset0:36 offset1:37
	s_waitcnt lgkmcnt(0)
	v_fma_f32 v22, v22, v0, -v70
	v_fma_f32 v23, v23, v0, -v71
	s_nop 0
	v_fma_f32 v68, v22, v22, v68
	v_fma_f32 v69, v23, v23, v69
	v_mul_f32_e32 v70, v23, v23
	v_add_f32_e32 v68, v68, v70
	v_add_f32_e32 v69, v69, v70
	ds_read2st64_b32 v[70:71], v66 offset0:38 offset1:39
	s_waitcnt lgkmcnt(0)
	v_fma_f32 v24, v24, v0, -v70
	v_fma_f32 v25, v25, v0, -v71
	s_nop 0
	v_fma_f32 v68, v24, v24, v68
	v_fma_f32 v69, v25, v25, v69
	v_mul_f32_e32 v70, v25, v25
	v_add_f32_e32 v68, v68, v70
	v_add_f32_e32 v69, v69, v70
	ds_read2st64_b32 v[70:71], v66 offset0:40 offset1:41
	s_waitcnt lgkmcnt(0)
	v_fma_f32 v26, v26, v0, -v70
	v_fma_f32 v27, v27, v0, -v71
	s_nop 0
	v_fma_f32 v68, v26, v26, v68
	v_fma_f32 v69, v27, v27, v69
	v_mul_f32_e32 v70, v27, v27
	v_add_f32_e32 v68, v68, v70
	v_add_f32_e32 v69, v69, v70
	ds_read2st64_b32 v[70:71], v66 offset0:42 offset1:43
	s_waitcnt lgkmcnt(0)
	v_fma_f32 v28, v28, v0, -v70
	v_fma_f32 v29, v29, v0, -v71
	s_nop 0
	v_fma_f32 v68, v28, v28, v68
	v_fma_f32 v69, v29, v29, v69
	v_mul_f32_e32 v70, v29, v29
	v_add_f32_e32 v68, v68, v70
	v_add_f32_e32 v69, v69, v70
	ds_read2st64_b32 v[70:71], v66 offset0:44 offset1:45
	s_waitcnt lgkmcnt(0)
	v_fma_f32 v30, v30, v0, -v70
	v_fma_f32 v31, v31, v0, -v71
	s_nop 0
	v_fma_f32 v68, v30, v30, v68
	v_fma_f32 v69, v31, v31, v69
	v_mul_f32_e32 v70, v31, v31
	v_add_f32_e32 v68, v68, v70
	v_add_f32_e32 v69, v69, v70
	ds_read2st64_b32 v[70:71], v66 offset0:46 offset1:47
	s_waitcnt lgkmcnt(0)
	v_fma_f32 v32, v32, v0, -v70
	v_fma_f32 v33, v33, v0, -v71
	s_nop 0
	v_fma_f32 v68, v32, v32, v68
	v_fma_f32 v69, v33, v33, v69
	v_mul_f32_e32 v70, v33, v33
	v_add_f32_e32 v68, v68, v70
	v_add_f32_e32 v69, v69, v70
	ds_read2st64_b32 v[70:71], v66 offset0:48 offset1:49
	s_waitcnt lgkmcnt(0)
	v_fma_f32 v2, v2, v0, -v70
	v_fma_f32 v3, v3, v0, -v71
	s_nop 0
	v_fma_f32 v68, v2, v2, v68
	v_fma_f32 v69, v3, v3, v69
	v_mul_f32_e32 v70, v3, v3
	v_add_f32_e32 v68, v68, v70
	v_add_f32_e32 v69, v69, v70
	ds_read2st64_b32 v[70:71], v66 offset0:50 offset1:51
	s_waitcnt lgkmcnt(0)
	v_fma_f32 v4, v4, v0, -v70
	v_fma_f32 v5, v5, v0, -v71
	s_nop 0
	v_fma_f32 v68, v4, v4, v68
	v_fma_f32 v69, v5, v5, v69
	v_mul_f32_e32 v70, v5, v5
	v_add_f32_e32 v68, v68, v70
	v_add_f32_e32 v69, v69, v70
	ds_read2st64_b32 v[70:71], v66 offset0:52 offset1:53
	s_waitcnt lgkmcnt(0)
	v_fma_f32 v6, v6, v0, -v70
	v_fma_f32 v7, v7, v0, -v71
	s_nop 0
	v_fma_f32 v68, v6, v6, v68
	v_fma_f32 v69, v7, v7, v69
	v_mul_f32_e32 v70, v7, v7
	v_add_f32_e32 v68, v68, v70
	v_add_f32_e32 v69, v69, v70
	ds_read2st64_b32 v[70:71], v66 offset0:54 offset1:55
	s_waitcnt lgkmcnt(0)
	v_fma_f32 v8, v8, v0, -v70
	v_fma_f32 v9, v9, v0, -v71
	s_nop 0
	v_fma_f32 v68, v8, v8, v68
	v_fma_f32 v69, v9, v9, v69
	v_mul_f32_e32 v70, v9, v9
	v_add_f32_e32 v68, v68, v70
	v_add_f32_e32 v69, v69, v70
	ds_read2st64_b32 v[70:71], v66 offset0:56 offset1:57
	s_waitcnt lgkmcnt(0)
	v_fma_f32 v10, v10, v0, -v70
	v_fma_f32 v11, v11, v0, -v71
	s_nop 0
	v_fma_f32 v68, v10, v10, v68
	v_fma_f32 v69, v11, v11, v69
	v_mul_f32_e32 v70, v11, v11
	v_add_f32_e32 v68, v68, v70
	v_add_f32_e32 v69, v69, v70
	ds_read2st64_b32 v[70:71], v66 offset0:58 offset1:59
	s_waitcnt lgkmcnt(0)
	v_fma_f32 v12, v12, v0, -v70
	v_fma_f32 v13, v13, v0, -v71
	s_nop 0
	v_fma_f32 v68, v12, v12, v68
	v_fma_f32 v69, v13, v13, v69
	v_mul_f32_e32 v70, v13, v13
	v_add_f32_e32 v68, v68, v70
	v_add_f32_e32 v69, v69, v70
	ds_read2st64_b32 v[70:71], v66 offset0:60 offset1:61
	ds_read2st64_b32 v[66:67], v66 offset0:62 offset1:63
	s_waitcnt lgkmcnt(1)
	v_fma_f32 v14, v14, v0, -v70
	v_fma_f32 v15, v15, v0, -v71
	s_nop 0
	v_fma_f32 v68, v14, v14, v68
	v_fma_f32 v69, v15, v15, v69
	v_mul_f32_e32 v70, v15, v15
	v_add_f32_e32 v68, v68, v70
	v_add_f32_e32 v69, v69, v70
	s_waitcnt lgkmcnt(0)
	v_fma_f32 v16, v16, v0, -v66
	v_fma_f32 v17, v17, v0, -v67
	s_nop 0
	v_fma_f32 v66, v16, v16, v68
	v_fma_f32 v67, v17, v17, v69
	v_mul_f32_e32 v0, v17, v17
	v_add_f32_e32 v66, v66, v0
	v_add_f32_e32 v67, v67, v0
	s_nop 0
	v_mov_b32_e32 v0, v66
	s_nop 1
	v_permlane32_swap_b32_e32 v66, v0
	v_add_f32_e32 v0, v66, v0
	v_fmamk_f32 v0, v0, 0x3c000000, v204
	v_rsq_f32_e32 v0, v0
	s_nop 0
	v_mul_f32_e32 v68, v121, v0

; __device__ __forceinline__ unsigned cvtpk(float lo, float hi) { unsigned r; asm("v_cvt_pk_bf16_f32 %0, %1, %2" : "=v"(r) : "v"(lo), "v"(hi)); return r; }
; template <bool MASKED>
; __device__ __forceinline__ void softmax_tile(f32x16& s0, f32x16& s1, float& m, float& l, float& alpha, unsigned mlo, unsigned mhi, bf16x8 (&pk)[4]) {
;     ...
;     float sum = 0.f;
; #pragma unroll
;     for (int r = 0; r < 16; ++r) {
;         float p0 = __builtin_amdgcn_exp2f(s0[r] - mn), p1 = __builtin_amdgcn_exp2f(s1[r] - mn);
;         if (MASKED) { if (s0[r] <= -1e29f) p0 = 0.f; if (s1[r] <= -1e29f) p1 = 0.f; }
;         s0[r] = p0; s1[r] = p1; sum += p0 + p1;
;     }
;     l = l * alpha + sum;
; #pragma unroll
;     for (int k2 = 0; k2 < 2; ++k2) {
;         u32x4 a, b;
;         a.x = cvtpk(s0[8 * k2 + 0], s0[8 * k2 + 1]); a.y = cvtpk(s0[8 * k2 + 2], s0[8 * k2 + 3]); a.z = cvtpk(s0[8 * k2 + 4], s0[8 * k2 + 5]); a.w = cvtpk(s0[8 * k2 + 6], s0[8 * k2 + 7]);
;         b.x = cvtpk(s1[8 * k2 + 0], s1[8 * k2 + 1]); b.y = cvtpk(s1[8 * k2 + 2], s1[8 * k2 + 3]); b.z = cvtpk(s1[8 * k2 + 4], s1[8 * k2 + 5]); b.w = cvtpk(s1[8 * k2 + 6], s1[8 * k2 + 7]);
;         pk[k2] = __builtin_bit_cast(bf16x8, a); pk[2 + k2] = __builtin_bit_cast(bf16x8, b);
;     }
.Lm1_cfast:
	v_exp_f32_e32 v82, v82
	v_exp_f32_e32 v83, v83
	v_exp_f32_e32 v84, v84
	v_exp_f32_e32 v85, v85
	v_exp_f32_e32 v86, v86
	v_exp_f32_e32 v87, v87
	v_exp_f32_e32 v88, v88
	v_exp_f32_e32 v89, v89
	v_exp_f32_e32 v90, v90
	v_exp_f32_e32 v91, v91
	v_exp_f32_e32 v92, v92
	v_exp_f32_e32 v93, v93
	v_exp_f32_e32 v94, v94
	v_exp_f32_e32 v95, v95
	v_exp_f32_e32 v96, v96
	v_exp_f32_e32 v97, v97
	v_exp_f32_e32 v66, v66
	v_exp_f32_e32 v67, v67
	v_exp_f32_e32 v68, v68
	v_exp_f32_e32 v69, v69
	v_exp_f32_e32 v70, v70
	v_exp_f32_e32 v71, v71
	v_exp_f32_e32 v72, v72
	v_exp_f32_e32 v73, v73
	v_exp_f32_e32 v74, v74
	v_exp_f32_e32 v75, v75
	v_exp_f32_e32 v76, v76
	v_exp_f32_e32 v77, v77
	v_exp_f32_e32 v78, v78
	v_exp_f32_e32 v79, v79
	v_exp_f32_e32 v80, v80
	v_exp_f32_e32 v81, v81
	v_add_f32_e32 v164, v82, v84
	v_add_f32_e32 v165, v83, v85
	v_add_f32_e32 v166, v86, v88
	v_add_f32_e32 v167, v87, v89
	v_add_f32_e32 v168, v90, v92
	v_add_f32_e32 v169, v91, v93
	v_add_f32_e32 v170, v94, v96
	v_add_f32_e32 v171, v95, v97
	v_add_f32_e32 v172, v66, v68
	v_add_f32_e32 v173, v67, v69
	v_add_f32_e32 v174, v70, v72
	v_add_f32_e32 v175, v71, v73
	v_add_f32_e32 v186, v74, v76
	v_add_f32_e32 v187, v75, v77
	v_add_f32_e32 v188, v78, v80
	v_add_f32_e32 v189, v79, v81
	v_add_f32_e32 v164, v164, v166
	v_add_f32_e32 v165, v165, v167
	v_add_f32_e32 v168, v168, v170
	v_add_f32_e32 v169, v169, v171
	v_add_f32_e32 v172, v172, v174
	v_add_f32_e32 v173, v173, v175
	v_add_f32_e32 v186, v186, v188
	v_add_f32_e32 v187, v187, v189
	v_add_f32_e32 v164, v164, v168
	v_add_f32_e32 v165, v165, v169
	v_add_f32_e32 v172, v172, v186
	v_add_f32_e32 v173, v173, v187
	v_add_f32_e32 v164, v164, v172
	v_add_f32_e32 v165, v165, v173
	v_add_f32_e32 v164, v164, v165
	v_cvt_pk_bf16_f32 v66, v66, v67
	v_cvt_pk_bf16_f32 v67, v68, v69
	v_cvt_pk_bf16_f32 v68, v70, v71
	v_cvt_pk_bf16_f32 v69, v72, v73
	v_cvt_pk_bf16_f32 v70, v74, v75
	v_cvt_pk_bf16_f32 v71, v76, v77
	v_cvt_pk_bf16_f32 v72, v78, v79
	v_cvt_pk_bf16_f32 v73, v80, v81
	v_cvt_pk_bf16_f32 v74, v82, v83
	v_cvt_pk_bf16_f32 v75, v84, v85
	v_cvt_pk_bf16_f32 v76, v86, v87
	v_cvt_pk_bf16_f32 v77, v88, v89
	v_cvt_pk_bf16_f32 v78, v90, v91
	v_cvt_pk_bf16_f32 v79, v92, v93
	v_cvt_pk_bf16_f32 v80, v94, v95
	v_cvt_pk_bf16_f32 v81, v96, v97
	v_fmac_f32_e32 v164, v183, v0
	v_mov_b32_e32 v83, v164
	v_mov_b32_e32 v82, v162
	v_cmp_neq_f32_e32 vcc, 1.0, v0
	s_cbranch_vccz .LBB0_1179
	v_mul_f32_e32 v64, v64, v0
	v_mul_f32_e32 v65, v65, v0
	v_mul_f32_e32 v62, v62, v0
	v_mul_f32_e32 v63, v63, v0
	v_mul_f32_e32 v60, v60, v0
	v_mul_f32_e32 v61, v61, v0
	v_mul_f32_e32 v58, v58, v0
	v_mul_f32_e32 v59, v59, v0
	v_mul_f32_e32 v56, v56, v0
	v_mul_f32_e32 v57, v57, v0
	v_mul_f32_e32 v54, v54, v0
	v_mul_f32_e32 v55, v55, v0
	v_mul_f32_e32 v52, v52, v0
	v_mul_f32_e32 v53, v53, v0
	v_mul_f32_e32 v50, v50, v0
	v_mul_f32_e32 v51, v51, v0
	v_mul_f32_e32 v48, v48, v0
	v_mul_f32_e32 v49, v49, v0
	v_mul_f32_e32 v46, v46, v0
	v_mul_f32_e32 v47, v47, v0
	v_mul_f32_e32 v44, v44, v0
	v_mul_f32_e32 v45, v45, v0
	v_mul_f32_e32 v42, v42, v0
	v_mul_f32_e32 v43, v43, v0
	v_mul_f32_e32 v40, v40, v0
	v_mul_f32_e32 v41, v41, v0
	v_mul_f32_e32 v38, v38, v0
	v_mul_f32_e32 v39, v39, v0
	v_mul_f32_e32 v36, v36, v0
	v_mul_f32_e32 v37, v37, v0
	v_mul_f32_e32 v34, v34, v0
	v_mul_f32_e32 v35, v35, v0
	v_mul_f32_e32 v32, v32, v0
	v_mul_f32_e32 v33, v33, v0
	v_mul_f32_e32 v30, v30, v0
	v_mul_f32_e32 v31, v31, v0
	v_mul_f32_e32 v28, v28, v0
	v_mul_f32_e32 v29, v29, v0
	v_mul_f32_e32 v26, v26, v0
	v_mul_f32_e32 v27, v27, v0
	v_mul_f32_e32 v24, v24, v0
	v_mul_f32_e32 v25, v25, v0
	v_mul_f32_e32 v22, v22, v0
	v_mul_f32_e32 v23, v23, v0
	v_mul_f32_e32 v20, v20, v0
	v_mul_f32_e32 v21, v21, v0
	v_mul_f32_e32 v18, v18, v0
	v_mul_f32_e32 v19, v19, v0
	v_mul_f32_e32 v16, v16, v0
	v_mul_f32_e32 v17, v17, v0
	v_mul_f32_e32 v14, v14, v0
	v_mul_f32_e32 v15, v15, v0
	v_mul_f32_e32 v12, v12, v0
	v_mul_f32_e32 v13, v13, v0
	v_mul_f32_e32 v10, v10, v0
	v_mul_f32_e32 v11, v11, v0
	v_mul_f32_e32 v8, v8, v0
	v_mul_f32_e32 v9, v9, v0
	v_mul_f32_e32 v6, v6, v0
	v_mul_f32_e32 v7, v7, v0
	v_mul_f32_e32 v4, v4, v0
	v_mul_f32_e32 v5, v5, v0
	v_mul_f32_e32 v2, v2, v0
	v_mul_f32_e32 v3, v3, v0

; #define LAS __attribute__((address_space(3)))
; template <int MODE>
; __device__ __forceinline__ void attn_unit(LAS char* lds, const AttnPtrs& A, int b, int qb) {
;     ...
;     const int tid = opaque_tid(), lane = tid & 63, r32 = lane & 31, hi = lane >> 5, wid = __builtin_amdgcn_readfirstlane(tid >> 6);
;     const int strm = (MODE == 2) ? (wid & 1) : 0;
;     const size_t rowbase = (size_t)b * SEQ; const int q0 = (MODE == 2) ? qb * 128 + (wid >> 1) * 32 : qb * 256 + wid * 32; const int cw = q0 >> 6, NT = (MODE == 2) ? 2 * qb + 2 : 4 * qb + 4;
;     const size_t qrow = rowbase + q0 + r32;
;     const bf16_t* ksrc[2]; const bf16_t* vsrc[2];
; #pragma unroll
;     for (int i = 0; i < 2; ++i) { const unsigned row = 4u * (2 * wid + i) + (lane >> 4), ch = (lane & 15) ^ (((row & 3) << 2) | ((row >> 2) & 3));
;         ksrc[i] = A.K + (rowbase + row) * A.ldk + ch * 8; vsrc[i] = A.V + (rowbase + row) * A.ldv + ch * 8; }
;     const bf16_t* k64src = nullptr;
;     if constexpr (MODE == 0) { const unsigned row = 8u * wid + (lane >> 3), ch = (lane & 7) ^ ((row >> 1) & 7); k64src = A.K64 + (rowbase + row) * 64 + ch * 8; }
;     const unsigned fK = ((r32 & 3) << 2) | ((r32 >> 2) & 3);
;     const unsigned g64 = (r32 >> 1) & 7;
;     const int q4 = (lane & 15) >> 2, p4 = lane & 3, blk = (lane >> 4) & 1;
;     unsigned vrow[2], vlow[2];
; #pragma unroll
;     for (int t = 0; t < 2; ++t) { vrow[t] = 4 * hi + 8 * t + q4; vlow[t] = (unsigned)((2 * blk + (p4 >> 1)) ^ ((hi + 2 * t) & 3)); }
;     ...
;     STAGE(0, 0); STAGE(1, 1);
;     bf16x8 qf[NQ];
; #pragma unroll
;     for (int s = 0; s < NQ; ++s) qf[s] = *(const bf16x8*)(A.Q + qrow * A.ldq + 64 * strm + 16 * s + 8 * hi);
;     ...
;                 const int qb = 15 - it / 44, w = it % 44;
;                 if (w < 24) { const int b = w / 6, h = w % 6;
;                     att::AttnPtrs A{QMLA + h * 192, NUQ, KMLA + h * 128, 768, KROPE, VMLA + h * 128, 768, GATE + h * 128, GATE + h * 128, nullptr, 0.f, 0.f, (const float*)TAB};
;     ...
;                     att::attn_unit<0>((LAS char*)lds, A, b, qb);
.LBB0_1186:
	s_and_b64 vcc, exec, s[0:1]
	s_cbranch_vccz .LBB0_1201
	s_bfe_i32 s0, s14, 0x80000
	s_mul_i32 s0, s0, 43
	s_bfe_u32 s1, s0, 0x1000f
	s_bfe_u32 s0, s0, 0x80008
	s_add_i32 s12, s0, s1
	s_mul_i32 s0, s12, 6
	s_sub_i32 s0, s14, s0
	s_sext_i32_i8 s13, s0
	s_mul_i32 s0, s13, 0xc0
	s_ashr_i32 s1, s0, 31
	s_lshl_b64 s[0:1], s[0:1], 1
	s_add_u32 s16, s29, s0
	s_addc_u32 s17, s34, s1
	s_lshl_b32 s0, s13, 7
	s_ashr_i32 s1, s0, 31
	s_lshl_b64 s[0:1], s[0:1], 1
	s_add_u32 s52, s35, s0
	s_addc_u32 s53, s44, s1
	s_add_u32 s54, s45, s0
	s_getreg_b32 s13, hwreg(HW_REG_HW_ID, 0, 6)
	s_addc_u32 s55, s46, s1
	s_lshl_b32 s13, s13, 2
	s_and_b32 s13, s13, 0xfc
	s_add_i32 s13, s13, 0x20040
	v_mov_b32_e32 v0, s13
	ds_read_b32 v0, v0
	s_lshl_b32 s51, s49, 8
	v_mov_b64_e32 v[6:7], s[52:53]
	v_mov_b32_e32 v3, v1
	s_mov_b32 s33, 2
	s_waitcnt lgkmcnt(0)
	v_readfirstlane_b32 s13, v0
	v_mov_b32_e32 v0, v1
	s_mov_b32 s50, 0
	v_mbcnt_lo_u32_b32 v0, -1, v0
	v_mbcnt_hi_u32_b32 v8, -1, v0
	v_lshl_or_b32 v11, s13, 6, v8
	v_bfe_u32 v10, v8, 4, 2
	v_readfirstlane_b32 s13, v11
	s_ashr_i32 s13, s13, 6
	s_bfe_i64 s[14:15], s[12:13], 0x80000
	s_lshl_b32 s56, s13, 5
	s_lshl_b32 s58, s13, 3
	s_lshl_b64 s[18:19], s[14:15], 12
	s_add_i32 s56, s56, s51
	s_lshl_b32 s51, s49, 2
	v_or_b32_e32 v0, s58, v10
	s_lshl_b32 s49, s13, 1
	v_and_b32_e32 v16, 15, v8
	v_lshlrev_b32_e32 v17, 2, v10
	s_and_b32 s49, s49, 2
	v_lshl_add_u64 v[4:5], s[18:19], 0, v[0:1]
	v_bitop3_b32 v2, s49, v16, v17 bitop3:0x36
	v_mad_u64_u32 v[12:13], s[52:53], v4, s20, v[6:7]
	v_mad_i32_i24 v13, v5, s20, v13
	v_lshlrev_b32_e32 v2, 4, v2
	v_lshl_add_u64 v[38:39], v[12:13], 0, v[2:3]
	v_mov_b64_e32 v[12:13], s[54:55]
	v_mad_u64_u32 v[14:15], s[52:53], v4, s20, v[12:13]
	s_or_b32 s49, s58, 4
	v_mad_i32_i24 v15, v5, s20, v15
	v_or_b32_e32 v4, s49, v10
	v_mov_b32_e32 v5, v1
	v_lshl_add_u64 v[40:41], v[14:15], 0, v[2:3]
	s_bfe_u32 s49, s49, 0x20002
	v_lshl_add_u64 v[14:15], s[18:19], 0, v[4:5]
	v_bitop3_b32 v10, s49, v16, v17 bitop3:0x36
	v_mad_u64_u32 v[6:7], s[52:53], v14, s20, v[6:7]
	v_mad_i32_i24 v7, v15, s20, v7
	v_lshlrev_b32_e32 v4, 4, v10
	s_ashr_i32 s57, s56, 31
	v_lshl_add_u64 v[42:43], v[6:7], 0, v[4:5]
	v_mad_u64_u32 v[6:7], s[52:53], v14, s20, v[12:13]
	s_ashr_i32 s49, s56, 6
	v_and_b32_e32 v9, 31, v8
	s_add_u32 s52, s18, s56
	v_mad_i32_i24 v7, v15, s20, v7
	v_or_b32_e32 v178, s52, v9
	v_mov_b64_e32 v[14:15], s[16:17]
	s_movk_i32 s16, 0x900
	v_mad_u64_u32 v[14:15], s[16:17], v178, s16, v[14:15]
	v_mad_u64_u32 v[18:19], s[16:17], v178, 56, 0
	v_lshl_add_u64 v[50:51], v[6:7], 0, v[4:5]
	v_bfe_u32 v12, v8, 5, 1
	s_addc_u32 s53, s19, s57
	v_mov_b32_e32 v7, 0x900
	v_mov_b32_e32 v20, v19
	v_lshlrev_b32_e32 v176, 2, v12
	v_mad_i32_i24 v15, s53, v7, v15
	v_lshlrev_b32_e32 v16, 4, v12
	v_mov_b32_e32 v17, v1
	v_mad_u64_u32 v[20:21], s[16:17], s53, 56, v[20:21]
	v_lshl_add_u64 v[52:53], v[14:15], 0, v[16:17]
	v_or_b32_e32 v18, v18, v176
	v_mov_b32_e32 v19, v20
	global_load_dwordx4 v[14:17], v[52:53], off offset:256
	v_lshl_add_u64 v[58:59], v[18:19], 3, s[10:11]
	global_load_dwordx4 v[18:21], v[58:59], off offset:16
	global_load_dwordx4 v[22:25], v[58:59], off
	v_bfe_u32 v6, v8, 3, 3
	v_or_b32_e32 v6, s58, v6
	v_lshrrev_b32_e32 v10, 1, v6
	v_mov_b32_e32 v7, v1
	s_lshl_b32 s16, s13, 11
	v_xor_b32_e32 v13, v10, v8
	v_lshl_add_u64 v[26:27], s[18:19], 0, v[6:7]
	v_lshrrev_b32_e32 v28, 3, v8
	s_add_i32 s16, s16, 0
	v_lshlrev_b64 v[26:27], 7, v[26:27]
	v_and_b32_e32 v28, 2, v28
	v_bfe_u32 v29, v11, 1, 1
	v_or_b32_e32 v67, 2, v12
	v_lshlrev_b32_e32 v13, 4, v13
	s_mov_b32 m0, s16
	v_lshlrev_b32_e32 v30, 2, v8
	v_or_b32_e32 v64, v29, v28
	v_bitop3_b32 v66, v29, v12, v28 bitop3:0x36
	v_bitop3_b32 v68, v29, v67, v28 bitop3:0x36
	v_lshl_add_u64 v[26:27], s[8:9], 0, v[26:27]
	v_and_b32_e32 v28, 0x70, v13
	v_mov_b32_e32 v29, v1
	global_load_lds_dwordx4 v[38:39], off
	v_lshl_add_u64 v[54:55], v[26:27], 0, v[28:29]
	v_and_b32_e32 v13, 12, v30
	global_load_dwordx4 v[26:29], v[52:53], off offset:288
	global_load_dwordx4 v[30:33], v[58:59], off offset:80
	global_load_dwordx4 v[34:37], v[58:59], off offset:64
	s_add_i32 m0, s16, 0x400
	s_lshl_b32 s13, s13, 10
	global_load_lds_dwordx4 v[42:43], off
	s_add_i32 m0, s16, 0x4000
	s_sub_i32 s17, s16, s13
	global_load_lds_dwordx4 v[40:41], off
	s_add_i32 m0, s16, 0x4400
	v_lshl_add_u64 v[38:39], v[38:39], 0, s[94:95]
	global_load_lds_dwordx4 v[50:51], off
	s_add_i32 m0, s17, 0x8000
	v_lshl_add_u64 v[56:57], v[40:41], 0, s[94:95]
	global_load_lds_dwordx4 v[54:55], off
	s_add_i32 m0, s16, 0xa000
	v_lshl_add_u64 v[50:51], v[50:51], 0, s[94:95]
	global_load_lds_dwordx4 v[38:39], off
	v_lshl_add_u64 v[38:39], v[42:43], 0, s[94:95]
	s_add_i32 m0, s16, 0xa400
	v_bfe_u32 v62, v8, 2, 2
	global_load_lds_dwordx4 v[38:39], off
	global_load_dwordx4 v[38:41], v[52:53], off offset:320
	s_nop 0
	global_load_dwordx4 v[42:45], v[58:59], off offset:144
	global_load_dwordx4 v[46:49], v[58:59], off offset:128
	s_add_i32 m0, s16, 0xe000
	v_lshlrev_b32_e32 v177, 7, v9
	global_load_lds_dwordx4 v[56:57], off
	s_add_i32 m0, s16, 0xe400
	v_lshlrev_b32_e32 v186, 8, v9
	global_load_lds_dwordx4 v[50:51], off
	v_lshl_add_u64 v[50:51], v[54:55], 0, s[38:39]
	s_add_i32 m0, s17, 0x12000
	v_lshlrev_b32_e32 v9, 3, v8
	global_load_lds_dwordx4 v[50:51], off
	global_load_dwordx4 v[112:115], v[52:53], off
	global_load_dwordx4 v[116:119], v[52:53], off offset:32
	global_load_dwordx4 v[120:123], v[52:53], off offset:64
	global_load_dwordx4 v[124:127], v[52:53], off offset:96
	global_load_dwordx4 v[128:131], v[52:53], off offset:128
	global_load_dwordx4 v[132:135], v[52:53], off offset:160
	global_load_dwordx4 v[136:139], v[52:53], off offset:192
	global_load_dwordx4 v[140:143], v[52:53], off offset:224
	s_nop 0
	global_load_dwordx4 v[50:53], v[52:53], off offset:352
	v_or_b32_e32 v69, v13, v62
	v_lshrrev_b32_e32 v63, 1, v11
	v_bfe_u32 v11, v11, 1, 3
	s_add_i32 s17, s51, 4
	s_add_i32 s18, s13, 0
	s_lshl_b64 s[14:15], s[14:15], 19
	s_add_u32 s14, s14, 0x1b914000
	s_addc_u32 s15, s15, 0
	v_lshlrev_b64 v[6:7], 7, v[6:7]
	v_lshl_add_u64 v[180:181], s[14:15], 0, v[6:7]
	s_waitcnt vmcnt(0)
; __device__ __forceinline__ unsigned cvtpk(float lo, float hi) { unsigned r; asm("v_cvt_pk_bf16_f32 %0, %1, %2" : "=v"(r) : "v"(lo), "v"(hi)); return r; }
; __device__ __forceinline__ float bf_lo(unsigned w) { return __uint_as_float(w << 16); }
; __device__ __forceinline__ float bf_hi(unsigned w) { return __uint_as_float(w & 0xffff0000u); }
; template <int MODE>
; __device__ __forceinline__ void attn_unit(LAS char* lds, const AttnPtrs& A, int b, int qb) {
;     ...
;     if constexpr (MODE == 0) {
; #pragma unroll
;         for (int s = 0; s < 4; ++s) {
;             const u32x4 w = __builtin_bit_cast(u32x4, qf[8 + s]);
;             const f32x4 t0 = *(const f32x4*)(A.subg + (qrow * 56 + 8 * s + 4 * hi) * 2), t1 = *(const f32x4*)(A.subg + (qrow * 56 + 8 * s + 4 * hi) * 2 + 4);
;             u32x4 o;
;             { const float a = bf_lo(w.x), b = bf_hi(w.x); o.x = cvtpk(a * t0[0] - b * t0[1], b * t0[0] + a * t0[1]); }
;             { const float a = bf_lo(w.y), b = bf_hi(w.y); o.y = cvtpk(a * t0[2] - b * t0[3], b * t0[2] + a * t0[3]); }
;             { const float a = bf_lo(w.z), b = bf_hi(w.z); o.z = cvtpk(a * t1[0] - b * t1[1], b * t1[0] + a * t1[1]); }
;             { const float a = bf_lo(w.w), b = bf_hi(w.w); o.w = cvtpk(a * t1[2] - b * t1[3], b * t1[2] + a * t1[3]); }
;             qf[8 + s] = __builtin_bit_cast(bf16x8, o);
;         }
;     }
	v_lshlrev_b32_e32 v54, 16, v14
	v_and_b32_e32 v55, 0xffff0000, v14
	v_mul_f32_e32 v56, v22, v54
	v_mul_f32_e32 v57, v23, v55
	v_mul_f32_e32 v22, v22, v55
	v_mul_f32_e32 v23, v23, v54
	v_sub_f32_e32 v14, v56, v57
	global_load_dwordx4 v[54:57], v[58:59], off offset:208
	s_nop 0
	global_load_dwordx4 v[58:61], v[58:59], off offset:192
	v_add_f32_e32 v22, v22, v23
	v_cvt_pk_bf16_f32 v144, v14, v22
	v_lshlrev_b32_e32 v14, 16, v15
	v_and_b32_e32 v15, 0xffff0000, v15
	v_mul_f32_e32 v22, v24, v14
	v_mul_f32_e32 v23, v25, v15
	v_pk_mul_f32 v[14:15], v[24:25], v[14:15] op_sel:[0,1] op_sel_hi:[1,0]
	v_sub_f32_e32 v22, v22, v23
	v_add_f32_e32 v14, v14, v15
	v_cvt_pk_bf16_f32 v145, v22, v14
	v_lshlrev_b32_e32 v14, 16, v16
	v_and_b32_e32 v15, 0xffff0000, v16
	v_mul_f32_e32 v22, v18, v14
	v_mul_f32_e32 v23, v19, v15
	v_pk_mul_f32 v[14:15], v[18:19], v[14:15] op_sel:[0,1] op_sel_hi:[1,0]
	v_sub_f32_e32 v16, v22, v23
	v_add_f32_e32 v14, v14, v15
	v_cvt_pk_bf16_f32 v146, v16, v14
	v_lshlrev_b32_e32 v14, 16, v17
	v_and_b32_e32 v15, 0xffff0000, v17
	v_mul_f32_e32 v16, v20, v14
	v_mul_f32_e32 v17, v21, v15
	v_pk_mul_f32 v[14:15], v[20:21], v[14:15] op_sel:[0,1] op_sel_hi:[1,0]
	v_sub_f32_e32 v16, v16, v17
	v_add_f32_e32 v14, v14, v15
	v_cvt_pk_bf16_f32 v147, v16, v14
	v_lshlrev_b32_e32 v14, 16, v26
	v_and_b32_e32 v15, 0xffff0000, v26
	v_mul_f32_e32 v16, v34, v14
	v_mul_f32_e32 v17, v35, v15
	v_pk_mul_f32 v[14:15], v[34:35], v[14:15] op_sel:[0,1] op_sel_hi:[1,0]
	v_sub_f32_e32 v16, v16, v17
	v_add_f32_e32 v14, v14, v15
	v_cvt_pk_bf16_f32 v148, v16, v14
	v_lshlrev_b32_e32 v14, 16, v27
	v_and_b32_e32 v15, 0xffff0000, v27
	v_mul_f32_e32 v16, v36, v14
	v_mul_f32_e32 v17, v37, v15
	v_pk_mul_f32 v[14:15], v[36:37], v[14:15] op_sel:[0,1] op_sel_hi:[1,0]
	v_sub_f32_e32 v16, v16, v17
	v_add_f32_e32 v14, v14, v15
	v_cvt_pk_bf16_f32 v149, v16, v14
	v_lshlrev_b32_e32 v14, 16, v28
	v_and_b32_e32 v15, 0xffff0000, v28
	v_mul_f32_e32 v16, v30, v14
	v_mul_f32_e32 v17, v31, v15
	v_pk_mul_f32 v[14:15], v[30:31], v[14:15] op_sel:[0,1] op_sel_hi:[1,0]
	v_sub_f32_e32 v16, v16, v17
	v_add_f32_e32 v14, v14, v15
	v_cvt_pk_bf16_f32 v150, v16, v14
	v_lshlrev_b32_e32 v14, 16, v29
	v_and_b32_e32 v15, 0xffff0000, v29
	v_mul_f32_e32 v16, v32, v14
	v_mul_f32_e32 v17, v33, v15
	v_pk_mul_f32 v[14:15], v[32:33], v[14:15] op_sel:[0,1] op_sel_hi:[1,0]
	v_sub_f32_e32 v16, v16, v17
	v_add_f32_e32 v14, v14, v15
	v_cvt_pk_bf16_f32 v151, v16, v14
	v_lshlrev_b32_e32 v14, 16, v38
	v_and_b32_e32 v15, 0xffff0000, v38
	v_mul_f32_e32 v16, v46, v14
	v_mul_f32_e32 v17, v47, v15
	v_pk_mul_f32 v[14:15], v[46:47], v[14:15] op_sel:[0,1] op_sel_hi:[1,0]
	v_sub_f32_e32 v16, v16, v17
	v_add_f32_e32 v14, v14, v15
	v_cvt_pk_bf16_f32 v152, v16, v14
	v_lshlrev_b32_e32 v14, 16, v39
	v_and_b32_e32 v15, 0xffff0000, v39
	v_mul_f32_e32 v16, v48, v14
	v_mul_f32_e32 v17, v49, v15
	v_pk_mul_f32 v[14:15], v[48:49], v[14:15] op_sel:[0,1] op_sel_hi:[1,0]
	v_sub_f32_e32 v16, v16, v17
	v_add_f32_e32 v14, v14, v15
	v_cvt_pk_bf16_f32 v153, v16, v14
	v_lshlrev_b32_e32 v14, 16, v40
	v_and_b32_e32 v15, 0xffff0000, v40
	v_mul_f32_e32 v16, v42, v14
	v_mul_f32_e32 v17, v43, v15
	v_pk_mul_f32 v[14:15], v[42:43], v[14:15] op_sel:[0,1] op_sel_hi:[1,0]
	v_sub_f32_e32 v16, v16, v17
	v_add_f32_e32 v14, v14, v15
	v_cvt_pk_bf16_f32 v154, v16, v14
	v_lshlrev_b32_e32 v14, 16, v41
	v_and_b32_e32 v15, 0xffff0000, v41
	v_mul_f32_e32 v16, v44, v14
	v_mul_f32_e32 v17, v45, v15
	v_pk_mul_f32 v[14:15], v[44:45], v[14:15] op_sel:[0,1] op_sel_hi:[1,0]
	v_sub_f32_e32 v16, v16, v17
	v_add_f32_e32 v14, v14, v15
	v_cvt_pk_bf16_f32 v155, v16, v14
	v_lshlrev_b32_e32 v14, 16, v50
	v_and_b32_e32 v15, 0xffff0000, v50
	s_waitcnt vmcnt(0)
	v_mul_f32_e32 v16, v58, v14
	v_mul_f32_e32 v17, v59, v15
	v_pk_mul_f32 v[14:15], v[58:59], v[14:15] op_sel:[0,1] op_sel_hi:[1,0]
	v_sub_f32_e32 v16, v16, v17
	v_add_f32_e32 v14, v14, v15
	v_cvt_pk_bf16_f32 v156, v16, v14
	v_lshlrev_b32_e32 v14, 16, v51
	v_and_b32_e32 v15, 0xffff0000, v51
	v_mul_f32_e32 v16, v60, v14
	v_mul_f32_e32 v17, v61, v15
	v_pk_mul_f32 v[14:15], v[60:61], v[14:15] op_sel:[0,1] op_sel_hi:[1,0]
	v_sub_f32_e32 v16, v16, v17
	v_add_f32_e32 v14, v14, v15
	v_cvt_pk_bf16_f32 v157, v16, v14
	v_lshlrev_b32_e32 v14, 16, v52
	v_and_b32_e32 v15, 0xffff0000, v52
	v_mul_f32_e32 v16, v54, v14
	v_mul_f32_e32 v17, v55, v15
	v_pk_mul_f32 v[14:15], v[54:55], v[14:15] op_sel:[0,1] op_sel_hi:[1,0]
	v_sub_f32_e32 v16, v16, v17
	v_add_f32_e32 v14, v14, v15
	v_cvt_pk_bf16_f32 v158, v16, v14
	v_lshlrev_b32_e32 v14, 16, v53
	v_and_b32_e32 v15, 0xffff0000, v53
	v_mul_f32_e32 v16, v56, v14
	v_mul_f32_e32 v17, v57, v15
	v_pk_mul_f32 v[14:15], v[56:57], v[14:15] op_sel:[0,1] op_sel_hi:[1,0]
	v_sub_f32_e32 v16, v16, v17
	v_add_f32_e32 v14, v14, v15
	v_cvt_pk_bf16_f32 v159, v16, v14
	v_mov_b32_e32 v14, 0x4000
	v_and_or_b32 v187, v9, 8, v14
	v_bitop3_b32 v9, v13, v12, v62 bitop3:0x36
	v_lshlrev_b32_e32 v188, 4, v9
	v_bitop3_b32 v9, v12, v69, 2 bitop3:0x36
	v_lshlrev_b32_e32 v189, 4, v9
	v_bitop3_b32 v9, v12, v69, 4 bitop3:0x36
	v_lshlrev_b32_e32 v190, 4, v9
	v_bitop3_b32 v9, v12, v69, 6 bitop3:0x36
	v_lshlrev_b32_e32 v191, 4, v9
	v_bitop3_b32 v9, v12, v69, 8 bitop3:0x36
	v_lshlrev_b32_e32 v192, 4, v9
	v_bitop3_b32 v9, v12, v69, 10 bitop3:0x36
	v_lshlrev_b32_e32 v193, 4, v9
	v_bitop3_b32 v9, v12, v69, 12 bitop3:0x36
	v_lshlrev_b32_e32 v194, 4, v9
	v_bitop3_b32 v9, v12, v69, 14 bitop3:0x36
	v_lshlrev_b32_e32 v195, 4, v9
	v_bitop3_b32 v9, v63, v12, 7 bitop3:0x6c
	v_lshlrev_b32_e32 v196, 4, v9
	v_bitop3_b32 v9, v12, v11, 2 bitop3:0x36
	v_lshlrev_b32_e32 v197, 4, v9
	v_bitop3_b32 v9, v12, v11, 4 bitop3:0x36
	v_lshlrev_b32_e32 v198, 4, v9
	v_bitop3_b32 v9, v12, v11, 6 bitop3:0x36
	v_lshlrev_b32_e32 v199, 4, v9
	v_and_b32_e32 v9, 12, v8
	v_or_b32_e32 v11, v66, v9
	v_or_b32_e32 v9, v68, v9
	v_lshlrev_b32_e32 v221, 4, v9
	v_bitop3_b32 v9, v8, 4, 12 bitop3:0x6c
	v_lshlrev_b32_e32 v219, 4, v11
	v_bitop3_b32 v11, v64, v9, v12 bitop3:0xde
	v_bitop3_b32 v9, v64, v9, v67 bitop3:0xde
	v_bitop3_b32 v6, v10, 7, v8 bitop3:0x48
	v_lshlrev_b32_e32 v229, 4, v9
	v_bitop3_b32 v9, v8, 8, 12 bitop3:0x6c
	v_lshl_or_b32 v180, v6, 4, v180
	v_or_b32_e32 v6, 4, v0
	v_lshlrev_b32_e32 v228, 4, v11
	v_bitop3_b32 v11, v64, v9, v12 bitop3:0xde
	v_bitop3_b32 v9, v64, v9, v67 bitop3:0xde
	v_mad_u64_u32 v[6:7], s[14:15], v6, s20, 0
	v_lshlrev_b32_e32 v231, 4, v9
	v_bitop3_b32 v9, v8, 12, v8 bitop3:0xc
	s_sext_i32_i8 s14, s12
	v_mov_b32_e32 v8, 0x600000
	v_mad_i64_i32 v[6:7], s[12:13], s14, v8, v[6:7]
	v_lshl_add_u64 v[4:5], v[6:7], 0, v[4:5]
	v_lshl_add_u64 v[182:183], v[4:5], 0, s[0:1]
	v_mad_u64_u32 v[4:5], s[12:13], v0, s20, 0
	v_mad_i64_i32 v[4:5], s[12:13], s14, v8, v[4:5]
	v_or_b32_e32 v65, v176, v62
	s_waitcnt vmcnt(0) lgkmcnt(0)
	s_barrier
; __device__ __forceinline__ unsigned cvtpk(float lo, float hi) { unsigned r; asm("v_cvt_pk_bf16_f32 %0, %1, %2" : "=v"(r) : "v"(lo), "v"(hi)); return r; }
; __device__ __forceinline__ float bf_lo(unsigned w) { return __uint_as_float(w << 16); }
; __device__ __forceinline__ float bf_hi(unsigned w) { return __uint_as_float(w & 0xffff0000u); }
; template <int MODE>
; __device__ __forceinline__ void attn_unit(LAS char* lds, const AttnPtrs& A, int b, int qb) {
;     ...
;     const unsigned fK = ((r32 & 3) << 2) | ((r32 >> 2) & 3);
;     const unsigned g64 = (r32 >> 1) & 7;
;     const int q4 = (lane & 15) >> 2, p4 = lane & 3, blk = (lane >> 4) & 1;
;     unsigned vrow[2], vlow[2];
; #pragma unroll
;     for (int t = 0; t < 2; ++t) { vrow[t] = 4 * hi + 8 * t + q4; vlow[t] = (unsigned)((2 * blk + (p4 >> 1)) ^ ((hi + 2 * t) & 3)); }
;     ...
;     STAGE(0, 0); STAGE(1, 1);
;     bf16x8 qf[NQ];
; #pragma unroll
;     for (int s = 0; s < NQ; ++s) qf[s] = *(const bf16x8*)(A.Q + qrow * A.ldq + 64 * strm + 16 * s + 8 * hi);
;     if constexpr (MODE == 0) {
; #pragma unroll
;         for (int s = 0; s < 4; ++s) {
;             const u32x4 w = __builtin_bit_cast(u32x4, qf[8 + s]);
;             const f32x4 t0 = *(const f32x4*)(A.subg + (qrow * 56 + 8 * s + 4 * hi) * 2), t1 = *(const f32x4*)(A.subg + (qrow * 56 + 8 * s + 4 * hi) * 2 + 4);
;             u32x4 o;
;             { const float a = bf_lo(w.x), b = bf_hi(w.x); o.x = cvtpk(a * t0[0] - b * t0[1], b * t0[0] + a * t0[1]); }
;             { const float a = bf_lo(w.y), b = bf_hi(w.y); o.y = cvtpk(a * t0[2] - b * t0[3], b * t0[2] + a * t0[3]); }
;             { const float a = bf_lo(w.z), b = bf_hi(w.z); o.z = cvtpk(a * t1[0] - b * t1[1], b * t1[0] + a * t1[1]); }
;             { const float a = bf_lo(w.w), b = bf_hi(w.w); o.w = cvtpk(a * t1[2] - b * t1[3], b * t1[2] + a * t1[3]); }
;             qf[8 + s] = __builtin_bit_cast(bf16x8, o);
;         }
;     }
; #pragma unroll
;     for (int s = 0; s < NQ; ++s) asm volatile("" :: "v"(qf[s]));
;     f32x16 o1[4];
; #pragma unroll
;     for (int c = 0; c < 4; ++c) o1[c] = f32x16{};
;     float m1 = -1e30f, l1 = 0.f;
;     unsigned long long mw_next = 0ull;
;     if constexpr (MODE == 1) { mw_next = A.MASK[qrow * 64]; asm volatile("" : "+v"(mw_next)); }
;     bf16x8 pk[4]; float a1 = 1.f;
	v_lshlrev_b32_e32 v230, 4, v11
	v_bitop3_b32 v11, v64, v9, v12 bitop3:0xde
	v_bitop3_b32 v9, v64, v9, v67 bitop3:0xde
	v_lshl_add_u64 v[2:3], v[4:5], 0, v[2:3]
	v_mov_b32_e32 v14, v1
	v_mov_b32_e32 v15, v1
	v_lshlrev_b32_e32 v218, 8, v65
	v_lshlrev_b32_e32 v232, 4, v11
	v_lshlrev_b32_e32 v233, 4, v9
	v_lshl_add_u64 v[184:185], v[2:3], 0, s[0:1]
	v_mov_b32_e32 v0, v1
	v_mov_b32_e32 v2, v1
	v_mov_b32_e32 v3, v1
	v_mov_b32_e32 v4, v1
	v_mov_b32_e32 v5, v1
	v_mov_b32_e32 v6, v1
	v_mov_b32_e32 v7, v1
	v_mov_b32_e32 v8, v1
	v_mov_b32_e32 v9, v1
	v_mov_b32_e32 v10, v1
	v_mov_b32_e32 v11, v1
	v_mov_b32_e32 v12, v1
	v_mov_b32_e32 v13, v1
	v_mov_b64_e32 v[30:31], v[14:15]
	v_mov_b64_e32 v[46:47], v[14:15]
	v_mov_b64_e32 v[62:63], v[14:15]
	v_mov_b64_e32 v[78:79], v[14:15]
	v_mov_b32_e32 v179, s53
	v_or_b32_e32 v220, 0x800, v218
	v_or_b32_e32 v222, 0x1000, v218
	v_or_b32_e32 v223, 0x1800, v218
	v_or_b32_e32 v224, 0x2000, v218
	v_or_b32_e32 v225, 0x2800, v218
	v_or_b32_e32 v226, 0x3000, v218
	v_or_b32_e32 v227, 0x3800, v218
	v_mov_b32_e32 v235, 0xf149f2ca
	v_mov_b32_e32 v253, s97
	v_mov_b32_e32 v252, 0
	v_mov_b64_e32 v[236:237], 0
	v_mov_b64_e32 v[238:239], 0
	v_mov_b64_e32 v[240:241], 0
	v_mov_b64_e32 v[242:243], 0
	v_mov_b64_e32 v[244:245], 0
	v_mov_b64_e32 v[246:247], 0
	v_mov_b64_e32 v[248:249], 0
	v_mov_b64_e32 v[250:251], 0
	v_mov_b32_e32 v234, 0
	v_mov_b64_e32 v[28:29], v[12:13]
	v_mov_b64_e32 v[26:27], v[10:11]
	v_mov_b64_e32 v[24:25], v[8:9]
	v_mov_b64_e32 v[22:23], v[6:7]
	v_mov_b64_e32 v[20:21], v[4:5]
	v_mov_b64_e32 v[18:19], v[2:3]
	v_mov_b64_e32 v[16:17], v[0:1]
	v_mov_b64_e32 v[44:45], v[12:13]
	v_mov_b64_e32 v[42:43], v[10:11]
	v_mov_b64_e32 v[40:41], v[8:9]
	v_mov_b64_e32 v[38:39], v[6:7]
	v_mov_b64_e32 v[36:37], v[4:5]
	v_mov_b64_e32 v[34:35], v[2:3]
	v_mov_b64_e32 v[32:33], v[0:1]
	v_mov_b64_e32 v[60:61], v[12:13]
	v_mov_b64_e32 v[58:59], v[10:11]
	v_mov_b64_e32 v[56:57], v[8:9]
	v_mov_b64_e32 v[54:55], v[6:7]
	v_mov_b64_e32 v[52:53], v[4:5]
	v_mov_b64_e32 v[50:51], v[2:3]
	v_mov_b64_e32 v[48:49], v[0:1]
	v_mov_b64_e32 v[76:77], v[12:13]
	v_mov_b64_e32 v[74:75], v[10:11]
	v_mov_b64_e32 v[72:73], v[8:9]
	v_mov_b64_e32 v[70:71], v[6:7]
	v_mov_b64_e32 v[68:69], v[4:5]
	v_mov_b64_e32 v[66:67], v[2:3]
	v_mov_b64_e32 v[64:65], v[0:1]
	s_mov_b32 s14, 0

; __device__ __forceinline__ unsigned cvtpk(float lo, float hi) { unsigned r; asm("v_cvt_pk_bf16_f32 %0, %1, %2" : "=v"(r) : "v"(lo), "v"(hi)); return r; }
; template <bool MASKED>
; __device__ __forceinline__ void softmax_tile(f32x16& s0, f32x16& s1, float& m, float& l, float& alpha, unsigned mlo, unsigned mhi, bf16x8 (&pk)[4]) {
;     ...
;     float sum = 0.f;
; #pragma unroll
;     for (int r = 0; r < 16; ++r) {
;         float p0 = __builtin_amdgcn_exp2f(s0[r] - mn), p1 = __builtin_amdgcn_exp2f(s1[r] - mn);
;         if (MASKED) { if (s0[r] <= -1e29f) p0 = 0.f; if (s1[r] <= -1e29f) p1 = 0.f; }
;         s0[r] = p0; s1[r] = p1; sum += p0 + p1;
;     }
;     l = l * alpha + sum;
; #pragma unroll
;     for (int k2 = 0; k2 < 2; ++k2) {
;         u32x4 a, b;
;         a.x = cvtpk(s0[8 * k2 + 0], s0[8 * k2 + 1]); a.y = cvtpk(s0[8 * k2 + 2], s0[8 * k2 + 3]); a.z = cvtpk(s0[8 * k2 + 4], s0[8 * k2 + 5]); a.w = cvtpk(s0[8 * k2 + 6], s0[8 * k2 + 7]);
;         b.x = cvtpk(s1[8 * k2 + 0], s1[8 * k2 + 1]); b.y = cvtpk(s1[8 * k2 + 2], s1[8 * k2 + 3]); b.z = cvtpk(s1[8 * k2 + 4], s1[8 * k2 + 5]); b.w = cvtpk(s1[8 * k2 + 6], s1[8 * k2 + 7]);
;         pk[k2] = __builtin_bit_cast(bf16x8, a); pk[2 + k2] = __builtin_bit_cast(bf16x8, b);
;     }
.Lm0_cfast:
	v_exp_f32_e32 v96, v96
	v_exp_f32_e32 v97, v97
	v_exp_f32_e32 v98, v98
	v_exp_f32_e32 v99, v99
	v_exp_f32_e32 v100, v100
	v_exp_f32_e32 v101, v101
	v_exp_f32_e32 v102, v102
	v_exp_f32_e32 v103, v103
	v_exp_f32_e32 v104, v104
	v_exp_f32_e32 v105, v105
	v_exp_f32_e32 v106, v106
	v_exp_f32_e32 v107, v107
	v_exp_f32_e32 v108, v108
	v_exp_f32_e32 v109, v109
	v_exp_f32_e32 v110, v110
	v_exp_f32_e32 v111, v111
	v_exp_f32_e32 v80, v80
	v_exp_f32_e32 v81, v81
	v_exp_f32_e32 v82, v82
	v_exp_f32_e32 v83, v83
	v_exp_f32_e32 v84, v84
	v_exp_f32_e32 v85, v85
	v_exp_f32_e32 v86, v86
	v_exp_f32_e32 v87, v87
	v_exp_f32_e32 v88, v88
	v_exp_f32_e32 v89, v89
	v_exp_f32_e32 v90, v90
	v_exp_f32_e32 v91, v91
	v_exp_f32_e32 v92, v92
	v_exp_f32_e32 v93, v93
	v_exp_f32_e32 v94, v94
	v_exp_f32_e32 v95, v95
	v_add_f32_e32 v160, v96, v98
	v_add_f32_e32 v161, v97, v99
	v_add_f32_e32 v162, v100, v102
	v_add_f32_e32 v163, v101, v103
	v_add_f32_e32 v164, v104, v106
	v_add_f32_e32 v165, v105, v107
	v_add_f32_e32 v166, v108, v110
	v_add_f32_e32 v167, v109, v111
	v_add_f32_e32 v168, v80, v82
	v_add_f32_e32 v169, v81, v83
	v_add_f32_e32 v170, v84, v86
	v_add_f32_e32 v171, v85, v87
	v_add_f32_e32 v172, v88, v90
	v_add_f32_e32 v173, v89, v91
	v_add_f32_e32 v174, v92, v94
	v_add_f32_e32 v175, v93, v95
	v_add_f32_e32 v160, v160, v162
	v_add_f32_e32 v161, v161, v163
	v_add_f32_e32 v164, v164, v166
	v_add_f32_e32 v165, v165, v167
	v_add_f32_e32 v168, v168, v170
	v_add_f32_e32 v169, v169, v171
	v_add_f32_e32 v172, v172, v174
	v_add_f32_e32 v173, v173, v175
	v_add_f32_e32 v160, v160, v164
	v_add_f32_e32 v161, v161, v165
	v_add_f32_e32 v168, v168, v172
	v_add_f32_e32 v169, v169, v173
	v_add_f32_e32 v160, v160, v168
	v_add_f32_e32 v161, v161, v169
	v_add_f32_e32 v15, v160, v161
	v_cvt_pk_bf16_f32 v2, v80, v81
	v_cvt_pk_bf16_f32 v3, v82, v83
	v_cvt_pk_bf16_f32 v4, v84, v85
	v_cvt_pk_bf16_f32 v5, v86, v87
	v_cvt_pk_bf16_f32 v6, v88, v89
	v_cvt_pk_bf16_f32 v7, v90, v91
	v_cvt_pk_bf16_f32 v8, v92, v93
	v_cvt_pk_bf16_f32 v9, v94, v95
	v_cvt_pk_bf16_f32 v80, v104, v105
	v_cvt_pk_bf16_f32 v81, v106, v107
	v_cvt_pk_bf16_f32 v82, v108, v109
	v_cvt_pk_bf16_f32 v83, v110, v111
	v_cvt_pk_bf16_f32 v10, v96, v97
	v_cvt_pk_bf16_f32 v11, v98, v99
	v_cvt_pk_bf16_f32 v12, v100, v101
	v_cvt_pk_bf16_f32 v13, v102, v103
	v_fmac_f32_e32 v15, v234, v0
	v_cmp_neq_f32_e32 vcc, 1.0, v0
	s_cbranch_vccz .LBB0_1193
	v_mul_f32_e32 v78, v78, v0
	v_mul_f32_e32 v79, v79, v0
	v_mul_f32_e32 v76, v76, v0
	v_mul_f32_e32 v77, v77, v0
	v_mul_f32_e32 v74, v74, v0
	v_mul_f32_e32 v75, v75, v0
	v_mul_f32_e32 v72, v72, v0
	v_mul_f32_e32 v73, v73, v0
	v_mul_f32_e32 v70, v70, v0
	v_mul_f32_e32 v71, v71, v0
	v_mul_f32_e32 v68, v68, v0
	v_mul_f32_e32 v69, v69, v0
	v_mul_f32_e32 v66, v66, v0
	v_mul_f32_e32 v67, v67, v0
	v_mul_f32_e32 v64, v64, v0
	v_mul_f32_e32 v65, v65, v0
	v_mul_f32_e32 v62, v62, v0
	v_mul_f32_e32 v63, v63, v0
	v_mul_f32_e32 v60, v60, v0
	v_mul_f32_e32 v61, v61, v0
	v_mul_f32_e32 v58, v58, v0
	v_mul_f32_e32 v59, v59, v0
	v_mul_f32_e32 v56, v56, v0
	v_mul_f32_e32 v57, v57, v0
	v_mul_f32_e32 v54, v54, v0
	v_mul_f32_e32 v55, v55, v0
	v_mul_f32_e32 v52, v52, v0
	v_mul_f32_e32 v53, v53, v0
	v_mul_f32_e32 v50, v50, v0
	v_mul_f32_e32 v51, v51, v0
	v_mul_f32_e32 v48, v48, v0
	v_mul_f32_e32 v49, v49, v0
	v_mul_f32_e32 v46, v46, v0
	v_mul_f32_e32 v47, v47, v0
	v_mul_f32_e32 v44, v44, v0
	v_mul_f32_e32 v45, v45, v0
	v_mul_f32_e32 v42, v42, v0
	v_mul_f32_e32 v43, v43, v0
	v_mul_f32_e32 v40, v40, v0
	v_mul_f32_e32 v41, v41, v0
	v_mul_f32_e32 v38, v38, v0
	v_mul_f32_e32 v39, v39, v0
	v_mul_f32_e32 v36, v36, v0
	v_mul_f32_e32 v37, v37, v0
	v_mul_f32_e32 v34, v34, v0
	v_mul_f32_e32 v35, v35, v0
	v_mul_f32_e32 v32, v32, v0
	v_mul_f32_e32 v33, v33, v0
	v_mul_f32_e32 v30, v30, v0
	v_mul_f32_e32 v31, v31, v0
	v_mul_f32_e32 v28, v28, v0
	v_mul_f32_e32 v29, v29, v0
	v_mul_f32_e32 v26, v26, v0
	v_mul_f32_e32 v27, v27, v0
	v_mul_f32_e32 v24, v24, v0
	v_mul_f32_e32 v25, v25, v0
	v_mul_f32_e32 v22, v22, v0
	v_mul_f32_e32 v23, v23, v0
	v_mul_f32_e32 v20, v20, v0
	v_mul_f32_e32 v21, v21, v0
	v_mul_f32_e32 v18, v18, v0
	v_mul_f32_e32 v19, v19, v0
	v_mul_f32_e32 v16, v16, v0
	v_mul_f32_e32 v17, v17, v0

;     ...
;         const int tid = opaque_tid();
;         const int gt = bx * 512 + tid, NGT = G * 512; const float* ss = ssqh;
;         for (int i = gt; i < TOK * DM / 4; i += NGT) { const int row = i / (DM / 4), c4 = i % (DM / 4);
;             const float r = __builtin_amdgcn_rsqf(pg8::sum_parts<8>(ss + (size_t)row * 32) * (1.0f / 2048.0f) + 1e-6f); const f32x4 gv = *(const f32x4*)(ap->final_g + c4 * 4);
;             const unsigned long long hw = *(const unsigned long long*)(HB + (size_t)i * 4); const unsigned w0 = (unsigned)hw, w1 = (unsigned)(hw >> 32);
;             f32x4 v = (f32x4){__uint_as_float(w0 << 16), __uint_as_float(w0 & 0xffff0000u), __uint_as_float(w1 << 16), __uint_as_float(w1 & 0xffff0000u)}; v = v * r * gv; *(f32x4*)(ap->out + (size_t)i * 4) = v; }
.LBB0_1418:
	v_ashrrev_i32_e32 v1, 31, v0
	v_lshrrev_b32_e32 v4, 23, v1
	v_add_u32_e32 v4, v0, v4
	v_ashrrev_i32_e32 v38, 9, v4
	v_ashrrev_i32_e32 v39, 31, v38
	v_lshlrev_b64 v[4:5], 7, v[38:39]
	v_lshl_add_u64 v[40:41], s[2:3], 0, v[4:5]
	v_lshl_add_u64 v[36:37], v[0:1], 3, s[8:9]
	global_load_dwordx4 v[4:7], v[40:41], off offset:48
	global_load_dwordx4 v[8:11], v[40:41], off offset:32
	global_load_dwordx4 v[12:15], v[40:41], off
	global_load_dwordx4 v[16:19], v[40:41], off offset:16
	global_load_dwordx4 v[20:23], v[40:41], off offset:112
	global_load_dwordx4 v[24:27], v[40:41], off offset:96
	global_load_dwordx4 v[28:31], v[40:41], off offset:80
	global_load_dwordx4 v[32:35], v[40:41], off offset:64
	global_load_dwordx2 v[42:43], v[36:37], off
	v_mul_i32_i24_e32 v36, 0x200, v38
	v_lshlrev_b32_e32 v36, 2, v36
	v_sub_u32_e32 v36, v2, v36
	v_ashrrev_i32_e32 v37, 31, v36
	v_lshl_add_u64 v[36:37], v[36:37], 2, s[4:5]
	global_load_dwordx4 v[36:39], v[36:37], off
	v_lshl_add_u64 v[40:41], v[0:1], 4, s[6:7]
	v_add_u32_e32 v0, s82, v0
	v_cmp_lt_i32_e32 vcc, s11, v0
	s_or_b64 s[0:1], vcc, s[0:1]
	v_add_u32_e32 v2, s10, v2
	s_waitcnt vmcnt(6)
	v_add_f32_e32 v14, v14, v18
	v_add_f32_e32 v15, v15, v19
	v_add_f32_e32 v12, v12, v16
	v_add_f32_e32 v13, v13, v17
	v_add_f32_e32 v10, v14, v10
	v_add_f32_e32 v11, v15, v11
	v_add_f32_e32 v8, v12, v8
	v_add_f32_e32 v9, v13, v9
	v_add_f32_e32 v6, v10, v6
	v_add_f32_e32 v7, v11, v7
	v_add_f32_e32 v4, v8, v4
	v_add_f32_e32 v5, v9, v5
	s_waitcnt vmcnt(2)
	v_add_f32_e32 v6, v6, v34
	v_add_f32_e32 v7, v7, v35
	v_add_f32_e32 v4, v4, v32
	v_add_f32_e32 v5, v5, v33
	v_add_f32_e32 v6, v6, v30
	v_add_f32_e32 v7, v7, v31
	v_add_f32_e32 v4, v4, v28
	v_add_f32_e32 v5, v5, v29
	v_add_f32_e32 v6, v6, v26
	v_add_f32_e32 v7, v7, v27
	v_add_f32_e32 v4, v4, v24
	v_add_f32_e32 v5, v5, v25
	v_add_f32_e32 v6, v6, v22
	v_add_f32_e32 v7, v7, v23
	v_add_f32_e32 v4, v4, v20
	v_add_f32_e32 v5, v5, v21
	s_waitcnt vmcnt(1)
	v_lshlrev_b32_e32 v44, 16, v42
	v_pk_mov_b32 v[8:9], v[4:5], v[6:7] op_sel:[1,0]
	v_mov_b32_e32 v5, v7
	v_add_f32_e32 v4, v8, v4
	v_add_f32_e32 v5, v9, v5
	v_and_b32_e32 v45, 0xffff0000, v42
	v_add_f32_e32 v1, v4, v5
	v_fmamk_f32 v1, v1, 0x3a000000, v3
	v_rsq_f32_e32 v4, v1
	v_lshlrev_b32_e32 v42, 16, v43
	v_and_b32_e32 v43, 0xffff0000, v43
	v_mul_f32_e32 v8, v4, v44
	v_mul_f32_e32 v9, v4, v45
	v_mul_f32_e32 v5, v4, v43
	v_mul_f32_e32 v4, v4, v42
	s_waitcnt vmcnt(0)
	v_mul_f32_e32 v6, v38, v4
	v_mul_f32_e32 v7, v39, v5
	v_mul_f32_e32 v4, v36, v8
	v_mul_f32_e32 v5, v37, v9
	global_store_dwordx4 v[40:41], v[4:7], off
	s_andn2_b64 exec, exec, s[0:1]
	s_cbranch_execnz .LBB0_1418
